# E6 + final-norm weight loads hoisted out of the row loop + in-proj rope epilogue: 4 rope-table loads per block issued together, block-entry store drain removed
# speedup vs baseline: 1.0065x; 1.0065x over previous
;     __device__ __forceinline__ void operator()(const f32x4 (&acc)[2][2][4][2], const Unit& u, int wr, int wc, int fr, int fq) const {
;     ...
;             const bool nrm = (pn < 15) || (wc < 2); const float* nw = (pn < 15) ? qnw : knw; const float sc = (pn < 15) ? C2 : 1.f;
;             f32x4 wv[2][2];
; #pragma unroll
;             for (int bj = 0; bj < 2; ++bj)
; #pragma unroll
;                 for (int n = 0; n < 2; ++n) wv[bj][n] = *(const f32x4*)(nw + 32 * bj + 8 * fq + 4 * n);
; #pragma unroll
;             for (int ai = 0; ai < 2; ++ai)
; #pragma unroll
;                 for (int m = 0; m < 4; ++m) { const int row = row0 + ai * HALF + m * 16; bf16_t* rowp = PROJ + (size_t)row * PP + pn * 256 + 64 * wc + 8 * fq;
;                     f32x4 v[2][2];
; #pragma unroll
;                     for (int bj = 0; bj < 2; ++bj)
; #pragma unroll
;                         for (int n = 0; n < 2; ++n) v[bj][n] = acc[ai][bj][m][n];
;                     if (nrm) {
;                         float ss = 0.f;
; #pragma unroll
;                         for (int bj = 0; bj < 2; ++bj)
; #pragma unroll
;                             for (int n = 0; n < 2; ++n) ss += v[bj][n][0] * v[bj][n][0] + v[bj][n][1] * v[bj][n][1] + v[bj][n][2] * v[bj][n][2] + v[bj][n][3] * v[bj][n][3];
;                         ss += __shfl_xor(ss, 16); ss += __shfl_xor(ss, 32);
;                         const float rinv = __builtin_amdgcn_rsqf(ss * (1.f / 64.f) + EPS);
; #pragma unroll
;                         for (int bj = 0; bj < 2; ++bj)
; #pragma unroll
;                             for (int n = 0; n < 2; ++n) { const f32x4 x = v[bj][n] * wv[bj][n] * rinv; const f32x4 cs = *(const f32x4*)(CS + ((size_t)row * 32 + 16 * bj + 4 * fq + 2 * n) * 2);
;                                 f32x4 o; o[0] = x[0] * cs[0] - x[1] * cs[1]; o[1] = x[0] * cs[1] + x[1] * cs[0]; o[2] = x[2] * cs[2] - x[3] * cs[3]; o[3] = x[2] * cs[3] + x[3] * cs[2]; v[bj][n] = o * sc; }
.LBB0_270:
	s_and_b64 vcc, exec, s[4:5]
	s_cbranch_vccz .LBB0_295
	s_cmp_lt_u32 s16, 15
	v_readlane_b32 s4, v255, 58
	s_cselect_b64 vcc, -1, 0
	v_readlane_b32 s5, v255, 59
	s_or_b64 s[56:57], vcc, s[4:5]
	s_and_b64 s[4:5], vcc, exec
	s_cselect_b32 s4, s12, s14
	s_cselect_b32 s5, s13, s15
	s_add_u32 s4, s4, s38
	v_lshlrev_b32_e32 v178, 3, v173
	s_addc_u32 s5, s5, s39
	v_ashrrev_i32_e32 v179, 31, v178
	v_lshl_add_u64 v[132:133], v[178:179], 2, s[4:5]
	global_load_dwordx4 v[136:139], v[132:133], off offset:16
	global_load_dwordx4 v[140:143], v[132:133], off
	global_load_dwordx4 v[128:131], v[132:133], off offset:144
	s_nop 0
	global_load_dwordx4 v[132:135], v[132:133], off offset:128
	v_cndmask_b32_e64 v144, 0, 1, s[56:57]
	v_cndmask_b32_e32 v176, 1.0, v233, vcc
	v_lshlrev_b32_e32 v182, 2, v173
	v_cmp_ne_u32_e64 s[4:5], 1, v144
	v_mov_b64_e32 v[154:155], v[98:99]
	v_mov_b64_e32 v[158:159], v[122:123]
	v_mov_b64_e32 v[150:151], v[90:91]
	v_mov_b64_e32 v[146:147], v[126:127]
	v_ashrrev_i32_e32 v183, 31, v182
	v_mov_b32_e32 v177, v176
	v_ashrrev_i32_e32 v181, 31, v180
	s_andn2_b64 vcc, exec, s[56:57]
	v_mov_b64_e32 v[152:153], v[96:97]
	v_mov_b64_e32 v[156:157], v[120:121]
	v_mov_b64_e32 v[148:149], v[88:89]
	v_mov_b64_e32 v[144:145], v[124:125]
	s_cbranch_vccnz .LBB0_273
	v_mov_b32_e32 v146, v125
	v_mov_b32_e32 v147, v89
	v_mov_b32_e32 v144, v124
	v_mov_b32_e32 v145, v88
	v_pk_mul_f32 v[146:147], v[146:147], v[146:147]
	v_mov_b32_e32 v148, v121
	v_pk_fma_f32 v[144:145], v[144:145], v[144:145], v[146:147]
	v_mov_b32_e32 v146, v126
	v_mov_b32_e32 v147, v90
	v_pk_fma_f32 v[144:145], v[146:147], v[146:147], v[144:145]
	v_mov_b32_e32 v146, v127
	v_mov_b32_e32 v147, v91
	v_mov_b32_e32 v149, v97
	v_pk_fma_f32 v[144:145], v[146:147], v[146:147], v[144:145]
	v_mov_b32_e32 v146, v120
	v_mov_b32_e32 v147, v96
	v_pk_mul_f32 v[148:149], v[148:149], v[148:149]
	v_add_f32_e32 v144, v144, v145
	v_pk_fma_f32 v[146:147], v[146:147], v[146:147], v[148:149]
	v_mov_b32_e32 v148, v122
	v_mov_b32_e32 v149, v98
	v_pk_fma_f32 v[146:147], v[148:149], v[148:149], v[146:147]
	v_mov_b32_e32 v148, v123
	v_mov_b32_e32 v149, v99
	v_pk_fma_f32 v[146:147], v[148:149], v[148:149], v[146:147]
	v_mov_b32_e32 v186, v176
	v_add_f32_e32 v144, v144, v146
	v_add_f32_e32 v144, v144, v147
	ds_bpermute_b32 v145, v196, v144
	s_waitcnt vmcnt(0)
	v_pk_mul_f32 v[146:147], v[124:125], v[140:141]
	v_mov_b32_e32 v187, v176
	s_waitcnt lgkmcnt(0)
	v_add_f32_e32 v144, v144, v145
	ds_bpermute_b32 v145, v197, v144
	s_waitcnt lgkmcnt(0)
	v_add_f32_e32 v144, v144, v145
	v_fmamk_f32 v144, v144, 0x3c800000, v253
	v_rsq_f32_e32 v184, v144
	v_pk_mul_f32 v[144:145], v[126:127], v[142:143]
	v_pk_mul_f32 v[154:155], v[146:147], v[184:185] op_sel_hi:[1,0]
	v_pk_mul_f32 v[152:153], v[144:145], v[184:185] op_sel_hi:[1,0]
	v_lshlrev_b64 v[144:145], 8, v[180:181]
	v_lshl_add_u64 v[144:145], s[22:23], 0, v[144:145]
	v_lshl_add_u64 v[156:157], v[182:183], 3, v[144:145]
	global_load_dwordx4 v[148:151], v[156:157], off offset:16
	global_load_dwordx4 v[144:147], v[156:157], off
	global_load_dwordx4 v[240:243], v[156:157], off offset:144
	global_load_dwordx4 v[244:247], v[156:157], off offset:128
	s_waitcnt vmcnt(0)
	v_pk_mul_f32 v[158:159], v[144:145], v[154:155] op_sel:[1,1] op_sel_hi:[0,1]
	v_pk_fma_f32 v[190:191], v[144:145], v[154:155], v[158:159] op_sel_hi:[1,0,1] neg_lo:[0,0,1] neg_hi:[0,0,1]
	v_pk_fma_f32 v[144:145], v[144:145], v[154:155], v[158:159] op_sel_hi:[1,0,1]
	v_pk_mul_f32 v[154:155], v[146:147], v[152:153] op_sel:[1,1] op_sel_hi:[0,1]
	v_pk_fma_f32 v[158:159], v[146:147], v[152:153], v[154:155] op_sel_hi:[1,0,1] neg_lo:[0,0,1] neg_hi:[0,0,1]
	v_pk_fma_f32 v[146:147], v[146:147], v[152:153], v[154:155] op_sel_hi:[1,0,1]
	v_pk_mul_f32 v[154:155], v[88:89], v[136:137]
	v_mov_b32_e32 v159, v147
	v_pk_mul_f32 v[152:153], v[90:91], v[138:139]
	v_pk_mul_f32 v[154:155], v[154:155], v[184:185] op_sel_hi:[1,0]
	v_pk_mul_f32 v[146:147], v[186:187], v[158:159]
	v_mov_b32_e32 v191, v145
	v_pk_mul_f32 v[152:153], v[152:153], v[184:185] op_sel_hi:[1,0]
	v_pk_mul_f32 v[158:159], v[148:149], v[154:155] op_sel:[1,1] op_sel_hi:[0,1]
	v_pk_mul_f32 v[144:145], v[176:177], v[190:191]
	v_pk_fma_f32 v[190:191], v[148:149], v[154:155], v[158:159] op_sel_hi:[1,0,1] neg_lo:[0,0,1] neg_hi:[0,0,1]
	v_pk_fma_f32 v[148:149], v[148:149], v[154:155], v[158:159] op_sel_hi:[1,0,1]
	v_pk_mul_f32 v[154:155], v[150:151], v[152:153] op_sel:[1,1] op_sel_hi:[0,1]
	v_pk_fma_f32 v[158:159], v[150:151], v[152:153], v[154:155] op_sel_hi:[1,0,1] neg_lo:[0,0,1] neg_hi:[0,0,1]
	v_pk_fma_f32 v[150:151], v[150:151], v[152:153], v[154:155] op_sel_hi:[1,0,1]
	v_mov_b32_e32 v191, v149
	v_mov_b32_e32 v159, v151
	v_pk_mul_f32 v[152:153], v[122:123], v[134:135]
	v_pk_mul_f32 v[154:155], v[120:121], v[132:133]
	v_pk_mul_f32 v[150:151], v[186:187], v[158:159]
	v_pk_mul_f32 v[148:149], v[176:177], v[190:191]
	v_pk_mul_f32 v[190:191], v[152:153], v[184:185] op_sel_hi:[1,0]
	v_pk_mul_f32 v[200:201], v[154:155], v[184:185] op_sel_hi:[1,0]
	v_mov_b64_e32 v[152:153], v[240:241]
	v_mov_b64_e32 v[154:155], v[242:243]
	v_mov_b64_e32 v[156:157], v[244:245]
	v_mov_b64_e32 v[158:159], v[246:247]
	v_pk_mul_f32 v[202:203], v[156:157], v[200:201] op_sel:[1,1] op_sel_hi:[0,1]
	v_pk_fma_f32 v[204:205], v[156:157], v[200:201], v[202:203] op_sel_hi:[1,0,1] neg_lo:[0,0,1] neg_hi:[0,0,1]
	v_pk_fma_f32 v[156:157], v[156:157], v[200:201], v[202:203] op_sel_hi:[1,0,1]
	v_pk_mul_f32 v[200:201], v[158:159], v[190:191] op_sel:[1,1] op_sel_hi:[0,1]
	v_pk_fma_f32 v[202:203], v[158:159], v[190:191], v[200:201] op_sel_hi:[1,0,1] neg_lo:[0,0,1] neg_hi:[0,0,1]
	v_pk_fma_f32 v[158:159], v[158:159], v[190:191], v[200:201] op_sel_hi:[1,0,1]
	v_pk_mul_f32 v[190:191], v[98:99], v[130:131]
	v_pk_mul_f32 v[200:201], v[96:97], v[128:129]
	v_pk_mul_f32 v[190:191], v[190:191], v[184:185] op_sel_hi:[1,0]
	v_pk_mul_f32 v[184:185], v[200:201], v[184:185] op_sel_hi:[1,0]
	v_mov_b32_e32 v203, v159
	v_pk_mul_f32 v[200:201], v[152:153], v[184:185] op_sel:[1,1] op_sel_hi:[0,1]
	v_pk_mul_f32 v[158:159], v[186:187], v[202:203]
	v_pk_fma_f32 v[202:203], v[152:153], v[184:185], v[200:201] op_sel_hi:[1,0,1] neg_lo:[0,0,1] neg_hi:[0,0,1]
	v_pk_fma_f32 v[152:153], v[152:153], v[184:185], v[200:201] op_sel_hi:[1,0,1]
	v_pk_mul_f32 v[184:185], v[154:155], v[190:191] op_sel:[1,1] op_sel_hi:[0,1]
	v_pk_fma_f32 v[200:201], v[154:155], v[190:191], v[184:185] op_sel_hi:[1,0,1] neg_lo:[0,0,1] neg_hi:[0,0,1]
	v_pk_fma_f32 v[154:155], v[154:155], v[190:191], v[184:185] op_sel_hi:[1,0,1]
	v_mov_b32_e32 v205, v157
	v_mov_b32_e32 v201, v155
	v_mov_b32_e32 v203, v153
	v_pk_mul_f32 v[156:157], v[176:177], v[204:205]
	v_pk_mul_f32 v[154:155], v[186:187], v[200:201]
	v_pk_mul_f32 v[152:153], v[176:177], v[202:203]
; __device__ __forceinline__ unsigned cvt_pk_bf16(float lo, float hi) { f32x2_c v = {lo, hi}; bf16x2_c b = __builtin_convertvector(v, bf16x2_c); return __builtin_bit_cast(unsigned, b); }
;     __device__ __forceinline__ void operator()(const f32x4 (&acc)[2][2][4][2], const Unit& u, int wr, int wc, int fr, int fq) const {
;     ...
;                 for (int m = 0; m < 4; ++m) { const int row = row0 + ai * HALF + m * 16; bf16_t* rowp = PROJ + (size_t)row * PP + pn * 256 + 64 * wc + 8 * fq;
;                     f32x4 v[2][2];
; #pragma unroll
;                     for (int bj = 0; bj < 2; ++bj)
; #pragma unroll
;                         for (int n = 0; n < 2; ++n) v[bj][n] = acc[ai][bj][m][n];
;                     if (nrm) {
;                         float ss = 0.f;
; #pragma unroll
;                         for (int bj = 0; bj < 2; ++bj)
; #pragma unroll
;                             for (int n = 0; n < 2; ++n) ss += v[bj][n][0] * v[bj][n][0] + v[bj][n][1] * v[bj][n][1] + v[bj][n][2] * v[bj][n][2] + v[bj][n][3] * v[bj][n][3];
;                         ss += __shfl_xor(ss, 16); ss += __shfl_xor(ss, 32);
;                         const float rinv = __builtin_amdgcn_rsqf(ss * (1.f / 64.f) + EPS);
; #pragma unroll
;                         for (int bj = 0; bj < 2; ++bj)
; #pragma unroll
;                             for (int n = 0; n < 2; ++n) { const f32x4 x = v[bj][n] * wv[bj][n] * rinv; const f32x4 cs = *(const f32x4*)(CS + ((size_t)row * 32 + 16 * bj + 4 * fq + 2 * n) * 2);
;                                 f32x4 o; o[0] = x[0] * cs[0] - x[1] * cs[1]; o[1] = x[0] * cs[1] + x[1] * cs[0]; o[2] = x[2] * cs[2] - x[3] * cs[3]; o[3] = x[2] * cs[3] + x[3] * cs[2]; v[bj][n] = o * sc; }
;                     }
; #pragma unroll
;                     for (int bj = 0; bj < 2; ++bj) { u32x4 w; w.x = cvt_pk_bf16(v[bj][0][0], v[bj][0][1]); w.y = cvt_pk_bf16(v[bj][0][2], v[bj][0][3]); w.z = cvt_pk_bf16(v[bj][1][0], v[bj][1][1]); w.w = cvt_pk_bf16(v[bj][1][2], v[bj][1][3]);
;                         *(u32x4*)(rowp + 32 * bj) = w; } }
.LBB0_273:
	v_mov_b64_e32 v[184:185], s[24:25]
	v_mad_i64_i32 v[184:185], s[56:57], v180, s64, v[184:185]
	s_lshl_b32 s78, s16, 9
	v_lshl_add_u64 v[184:185], v[184:185], 0, s[78:79]
	s_lshl_b32 s78, s81, 1
	v_lshl_add_u64 v[184:185], v[184:185], 0, s[78:79]
	v_lshl_add_u64 v[184:185], v[178:179], 1, v[184:185]
	v_cvt_pk_bf16_f32 v144, v144, v145
	v_cvt_pk_bf16_f32 v145, v146, v147
	v_cvt_pk_bf16_f32 v146, v148, v149
	v_cvt_pk_bf16_f32 v147, v150, v151
	global_store_dwordx4 v[184:185], v[144:147], off
	v_mov_b64_e32 v[150:151], v[82:83]
	s_and_b64 vcc, exec, s[4:5]
	v_cvt_pk_bf16_f32 v144, v156, v157
	v_cvt_pk_bf16_f32 v145, v158, v159
	v_cvt_pk_bf16_f32 v146, v152, v153
	v_cvt_pk_bf16_f32 v147, v154, v155
	global_store_dwordx4 v[184:185], v[144:147], off offset:64
	v_add_u32_e32 v184, 16, v180
	v_mov_b64_e32 v[154:155], v[86:87]
	v_mov_b64_e32 v[158:159], v[114:115]
	v_mov_b64_e32 v[146:147], v[118:119]
	v_ashrrev_i32_e32 v185, 31, v184
	v_mov_b64_e32 v[152:153], v[84:85]
	v_mov_b64_e32 v[156:157], v[112:113]
	v_mov_b64_e32 v[148:149], v[80:81]
	v_mov_b64_e32 v[144:145], v[116:117]
	s_cbranch_vccnz .LBB0_275
	v_mov_b32_e32 v146, v117
	v_mov_b32_e32 v147, v81
	v_mov_b32_e32 v144, v116
	v_mov_b32_e32 v145, v80
	v_pk_mul_f32 v[146:147], v[146:147], v[146:147]
	v_mov_b32_e32 v148, v113
	v_pk_fma_f32 v[144:145], v[144:145], v[144:145], v[146:147]
	v_mov_b32_e32 v146, v118
	v_mov_b32_e32 v147, v82
	v_pk_fma_f32 v[144:145], v[146:147], v[146:147], v[144:145]
	v_mov_b32_e32 v146, v119
	v_mov_b32_e32 v147, v83
	v_mov_b32_e32 v149, v85
	v_pk_fma_f32 v[144:145], v[146:147], v[146:147], v[144:145]
	v_mov_b32_e32 v146, v112
	v_mov_b32_e32 v147, v84
	v_pk_mul_f32 v[148:149], v[148:149], v[148:149]
	v_add_f32_e32 v144, v144, v145
	v_pk_fma_f32 v[146:147], v[146:147], v[146:147], v[148:149]
	v_mov_b32_e32 v148, v114
	v_mov_b32_e32 v149, v86
	v_pk_fma_f32 v[146:147], v[148:149], v[148:149], v[146:147]
	v_mov_b32_e32 v148, v115
	v_mov_b32_e32 v149, v87
	v_pk_fma_f32 v[146:147], v[148:149], v[148:149], v[146:147]
	v_mov_b32_e32 v190, v176
	v_add_f32_e32 v144, v144, v146
	v_add_f32_e32 v144, v144, v147
	ds_bpermute_b32 v145, v196, v144
	v_pk_mul_f32 v[146:147], v[116:117], v[140:141]
	v_mov_b32_e32 v191, v176
	s_waitcnt lgkmcnt(0)
	v_add_f32_e32 v144, v144, v145
	ds_bpermute_b32 v145, v197, v144
	s_waitcnt lgkmcnt(0)
	v_add_f32_e32 v144, v144, v145
	v_fmamk_f32 v144, v144, 0x3c800000, v253
	v_rsq_f32_e32 v186, v144
	v_pk_mul_f32 v[144:145], v[118:119], v[142:143]
	v_pk_mul_f32 v[154:155], v[146:147], v[186:187] op_sel_hi:[1,0]
	v_pk_mul_f32 v[152:153], v[144:145], v[186:187] op_sel_hi:[1,0]
	v_lshlrev_b64 v[144:145], 8, v[184:185]
	v_lshl_add_u64 v[144:145], s[22:23], 0, v[144:145]
	v_lshl_add_u64 v[156:157], v[182:183], 3, v[144:145]
	global_load_dwordx4 v[148:151], v[156:157], off offset:16
	global_load_dwordx4 v[144:147], v[156:157], off
	global_load_dwordx4 v[240:243], v[156:157], off offset:144
	global_load_dwordx4 v[244:247], v[156:157], off offset:128
	s_waitcnt vmcnt(0)
	v_pk_mul_f32 v[158:159], v[144:145], v[154:155] op_sel:[1,1] op_sel_hi:[0,1]
	v_pk_fma_f32 v[200:201], v[144:145], v[154:155], v[158:159] op_sel_hi:[1,0,1] neg_lo:[0,0,1] neg_hi:[0,0,1]
	v_pk_fma_f32 v[144:145], v[144:145], v[154:155], v[158:159] op_sel_hi:[1,0,1]
	v_pk_mul_f32 v[154:155], v[146:147], v[152:153] op_sel:[1,1] op_sel_hi:[0,1]
	v_pk_fma_f32 v[158:159], v[146:147], v[152:153], v[154:155] op_sel_hi:[1,0,1] neg_lo:[0,0,1] neg_hi:[0,0,1]
	v_pk_fma_f32 v[146:147], v[146:147], v[152:153], v[154:155] op_sel_hi:[1,0,1]
	v_pk_mul_f32 v[154:155], v[80:81], v[136:137]
	v_mov_b32_e32 v159, v147
	v_pk_mul_f32 v[152:153], v[82:83], v[138:139]
	v_pk_mul_f32 v[154:155], v[154:155], v[186:187] op_sel_hi:[1,0]
	v_pk_mul_f32 v[146:147], v[190:191], v[158:159]
	v_mov_b32_e32 v201, v145
	v_pk_mul_f32 v[152:153], v[152:153], v[186:187] op_sel_hi:[1,0]
	v_pk_mul_f32 v[158:159], v[148:149], v[154:155] op_sel:[1,1] op_sel_hi:[0,1]
	v_pk_mul_f32 v[144:145], v[176:177], v[200:201]
	v_pk_fma_f32 v[200:201], v[148:149], v[154:155], v[158:159] op_sel_hi:[1,0,1] neg_lo:[0,0,1] neg_hi:[0,0,1]
	v_pk_fma_f32 v[148:149], v[148:149], v[154:155], v[158:159] op_sel_hi:[1,0,1]
	v_pk_mul_f32 v[154:155], v[150:151], v[152:153] op_sel:[1,1] op_sel_hi:[0,1]
	v_pk_fma_f32 v[158:159], v[150:151], v[152:153], v[154:155] op_sel_hi:[1,0,1] neg_lo:[0,0,1] neg_hi:[0,0,1]
	v_pk_fma_f32 v[150:151], v[150:151], v[152:153], v[154:155] op_sel_hi:[1,0,1]
	v_mov_b32_e32 v201, v149
	v_mov_b32_e32 v159, v151
	v_pk_mul_f32 v[152:153], v[114:115], v[134:135]
	v_pk_mul_f32 v[154:155], v[112:113], v[132:133]
	v_pk_mul_f32 v[150:151], v[190:191], v[158:159]
	v_pk_mul_f32 v[148:149], v[176:177], v[200:201]
	v_pk_mul_f32 v[200:201], v[152:153], v[186:187] op_sel_hi:[1,0]
	v_pk_mul_f32 v[202:203], v[154:155], v[186:187] op_sel_hi:[1,0]
	v_mov_b64_e32 v[152:153], v[240:241]
	v_mov_b64_e32 v[154:155], v[242:243]
	v_mov_b64_e32 v[156:157], v[244:245]
	v_mov_b64_e32 v[158:159], v[246:247]
	v_pk_mul_f32 v[204:205], v[156:157], v[202:203] op_sel:[1,1] op_sel_hi:[0,1]
	v_pk_fma_f32 v[206:207], v[156:157], v[202:203], v[204:205] op_sel_hi:[1,0,1] neg_lo:[0,0,1] neg_hi:[0,0,1]
	v_pk_fma_f32 v[156:157], v[156:157], v[202:203], v[204:205] op_sel_hi:[1,0,1]
	v_pk_mul_f32 v[202:203], v[158:159], v[200:201] op_sel:[1,1] op_sel_hi:[0,1]
	v_pk_fma_f32 v[204:205], v[158:159], v[200:201], v[202:203] op_sel_hi:[1,0,1] neg_lo:[0,0,1] neg_hi:[0,0,1]
	v_pk_fma_f32 v[158:159], v[158:159], v[200:201], v[202:203] op_sel_hi:[1,0,1]
	v_pk_mul_f32 v[200:201], v[86:87], v[130:131]
	v_pk_mul_f32 v[202:203], v[84:85], v[128:129]
	v_pk_mul_f32 v[200:201], v[200:201], v[186:187] op_sel_hi:[1,0]
	v_pk_mul_f32 v[186:187], v[202:203], v[186:187] op_sel_hi:[1,0]
	v_mov_b32_e32 v205, v159
	v_pk_mul_f32 v[202:203], v[152:153], v[186:187] op_sel:[1,1] op_sel_hi:[0,1]
	v_pk_mul_f32 v[158:159], v[190:191], v[204:205]
	v_pk_fma_f32 v[204:205], v[152:153], v[186:187], v[202:203] op_sel_hi:[1,0,1] neg_lo:[0,0,1] neg_hi:[0,0,1]
	v_pk_fma_f32 v[152:153], v[152:153], v[186:187], v[202:203] op_sel_hi:[1,0,1]
	v_pk_mul_f32 v[186:187], v[154:155], v[200:201] op_sel:[1,1] op_sel_hi:[0,1]
	v_pk_fma_f32 v[202:203], v[154:155], v[200:201], v[186:187] op_sel_hi:[1,0,1] neg_lo:[0,0,1] neg_hi:[0,0,1]
	v_pk_fma_f32 v[154:155], v[154:155], v[200:201], v[186:187] op_sel_hi:[1,0,1]
	v_mov_b32_e32 v207, v157
	v_mov_b32_e32 v203, v155
	v_mov_b32_e32 v205, v153
	v_pk_mul_f32 v[156:157], v[176:177], v[206:207]
	v_pk_mul_f32 v[154:155], v[190:191], v[202:203]
	v_pk_mul_f32 v[152:153], v[176:177], v[204:205]
; __device__ __forceinline__ unsigned cvt_pk_bf16(float lo, float hi) { f32x2_c v = {lo, hi}; bf16x2_c b = __builtin_convertvector(v, bf16x2_c); return __builtin_bit_cast(unsigned, b); }
;     __device__ __forceinline__ void operator()(const f32x4 (&acc)[2][2][4][2], const Unit& u, int wr, int wc, int fr, int fq) const {
;     ...
;                 for (int m = 0; m < 4; ++m) { const int row = row0 + ai * HALF + m * 16; bf16_t* rowp = PROJ + (size_t)row * PP + pn * 256 + 64 * wc + 8 * fq;
;                     f32x4 v[2][2];
; #pragma unroll
;                     for (int bj = 0; bj < 2; ++bj)
; #pragma unroll
;                         for (int n = 0; n < 2; ++n) v[bj][n] = acc[ai][bj][m][n];
;                     if (nrm) {
;                         float ss = 0.f;
; #pragma unroll
;                         for (int bj = 0; bj < 2; ++bj)
; #pragma unroll
;                             for (int n = 0; n < 2; ++n) ss += v[bj][n][0] * v[bj][n][0] + v[bj][n][1] * v[bj][n][1] + v[bj][n][2] * v[bj][n][2] + v[bj][n][3] * v[bj][n][3];
;                         ss += __shfl_xor(ss, 16); ss += __shfl_xor(ss, 32);
;                         const float rinv = __builtin_amdgcn_rsqf(ss * (1.f / 64.f) + EPS);
; #pragma unroll
;                         for (int bj = 0; bj < 2; ++bj)
; #pragma unroll
;                             for (int n = 0; n < 2; ++n) { const f32x4 x = v[bj][n] * wv[bj][n] * rinv; const f32x4 cs = *(const f32x4*)(CS + ((size_t)row * 32 + 16 * bj + 4 * fq + 2 * n) * 2);
;                                 f32x4 o; o[0] = x[0] * cs[0] - x[1] * cs[1]; o[1] = x[0] * cs[1] + x[1] * cs[0]; o[2] = x[2] * cs[2] - x[3] * cs[3]; o[3] = x[2] * cs[3] + x[3] * cs[2]; v[bj][n] = o * sc; }
;                     }
; #pragma unroll
;                     for (int bj = 0; bj < 2; ++bj) { u32x4 w; w.x = cvt_pk_bf16(v[bj][0][0], v[bj][0][1]); w.y = cvt_pk_bf16(v[bj][0][2], v[bj][0][3]); w.z = cvt_pk_bf16(v[bj][1][0], v[bj][1][1]); w.w = cvt_pk_bf16(v[bj][1][2], v[bj][1][3]);
;                         *(u32x4*)(rowp + 32 * bj) = w; } }
.LBB0_275:
	v_mov_b64_e32 v[186:187], s[24:25]
	s_lshl_b32 s7, s16, 8
	v_mad_i64_i32 v[184:185], s[56:57], v184, s64, v[186:187]
	s_lshl_b32 s56, s7, 1
	s_mov_b32 s57, s79
	v_lshl_add_u64 v[184:185], v[184:185], 0, s[56:57]
	v_lshl_add_u64 v[184:185], v[184:185], 0, s[78:79]
	v_lshl_add_u64 v[184:185], v[178:179], 1, v[184:185]
	v_cvt_pk_bf16_f32 v144, v144, v145
	v_cvt_pk_bf16_f32 v145, v146, v147
	v_cvt_pk_bf16_f32 v146, v148, v149
	v_cvt_pk_bf16_f32 v147, v150, v151
	global_store_dwordx4 v[184:185], v[144:147], off
	v_mov_b64_e32 v[150:151], v[74:75]
	s_and_b64 vcc, exec, s[4:5]
	v_cvt_pk_bf16_f32 v144, v156, v157
	v_cvt_pk_bf16_f32 v145, v158, v159
	v_cvt_pk_bf16_f32 v146, v152, v153
	v_cvt_pk_bf16_f32 v147, v154, v155
	global_store_dwordx4 v[184:185], v[144:147], off offset:64
	v_add_u32_e32 v184, 32, v180
	v_mov_b64_e32 v[154:155], v[78:79]
	v_mov_b64_e32 v[158:159], v[106:107]
	v_mov_b64_e32 v[146:147], v[110:111]
	v_ashrrev_i32_e32 v185, 31, v184
	v_mov_b64_e32 v[152:153], v[76:77]
	v_mov_b64_e32 v[156:157], v[104:105]
	v_mov_b64_e32 v[148:149], v[72:73]
	v_mov_b64_e32 v[144:145], v[108:109]
	s_cbranch_vccnz .LBB0_277
	v_mov_b32_e32 v146, v109
	v_mov_b32_e32 v147, v73
	v_mov_b32_e32 v144, v108
	v_mov_b32_e32 v145, v72
	v_pk_mul_f32 v[146:147], v[146:147], v[146:147]
	v_mov_b32_e32 v148, v105
	v_pk_fma_f32 v[144:145], v[144:145], v[144:145], v[146:147]
	v_mov_b32_e32 v146, v110
	v_mov_b32_e32 v147, v74
	v_pk_fma_f32 v[144:145], v[146:147], v[146:147], v[144:145]
	v_mov_b32_e32 v146, v111
	v_mov_b32_e32 v147, v75
	v_mov_b32_e32 v149, v77
	v_pk_fma_f32 v[144:145], v[146:147], v[146:147], v[144:145]
	v_mov_b32_e32 v146, v104
	v_mov_b32_e32 v147, v76
	v_pk_mul_f32 v[148:149], v[148:149], v[148:149]
	v_add_f32_e32 v144, v144, v145
	v_pk_fma_f32 v[146:147], v[146:147], v[146:147], v[148:149]
	v_mov_b32_e32 v148, v106
	v_mov_b32_e32 v149, v78
	v_pk_fma_f32 v[146:147], v[148:149], v[148:149], v[146:147]
	v_mov_b32_e32 v148, v107
	v_mov_b32_e32 v149, v79
	v_pk_fma_f32 v[146:147], v[148:149], v[148:149], v[146:147]
	v_mov_b32_e32 v190, v176
	v_add_f32_e32 v144, v144, v146
	v_add_f32_e32 v144, v144, v147
	ds_bpermute_b32 v145, v196, v144
	v_pk_mul_f32 v[146:147], v[108:109], v[140:141]
	v_mov_b32_e32 v191, v176
	s_waitcnt lgkmcnt(0)
	v_add_f32_e32 v144, v144, v145
	ds_bpermute_b32 v145, v197, v144
	s_waitcnt lgkmcnt(0)
	v_add_f32_e32 v144, v144, v145
	v_fmamk_f32 v144, v144, 0x3c800000, v253
	v_rsq_f32_e32 v186, v144
	v_pk_mul_f32 v[144:145], v[110:111], v[142:143]
	v_pk_mul_f32 v[154:155], v[146:147], v[186:187] op_sel_hi:[1,0]
	v_pk_mul_f32 v[152:153], v[144:145], v[186:187] op_sel_hi:[1,0]
	v_lshlrev_b64 v[144:145], 8, v[184:185]
	v_lshl_add_u64 v[144:145], s[22:23], 0, v[144:145]
	v_lshl_add_u64 v[156:157], v[182:183], 3, v[144:145]
	global_load_dwordx4 v[148:151], v[156:157], off offset:16
	global_load_dwordx4 v[144:147], v[156:157], off
	global_load_dwordx4 v[240:243], v[156:157], off offset:144
	global_load_dwordx4 v[244:247], v[156:157], off offset:128
	s_waitcnt vmcnt(0)
	v_pk_mul_f32 v[158:159], v[144:145], v[154:155] op_sel:[1,1] op_sel_hi:[0,1]
	v_pk_fma_f32 v[200:201], v[144:145], v[154:155], v[158:159] op_sel_hi:[1,0,1] neg_lo:[0,0,1] neg_hi:[0,0,1]
	v_pk_fma_f32 v[144:145], v[144:145], v[154:155], v[158:159] op_sel_hi:[1,0,1]
	v_pk_mul_f32 v[154:155], v[146:147], v[152:153] op_sel:[1,1] op_sel_hi:[0,1]
	v_pk_fma_f32 v[158:159], v[146:147], v[152:153], v[154:155] op_sel_hi:[1,0,1] neg_lo:[0,0,1] neg_hi:[0,0,1]
	v_pk_fma_f32 v[146:147], v[146:147], v[152:153], v[154:155] op_sel_hi:[1,0,1]
	v_pk_mul_f32 v[154:155], v[72:73], v[136:137]
	v_mov_b32_e32 v159, v147
	v_pk_mul_f32 v[152:153], v[74:75], v[138:139]
	v_pk_mul_f32 v[154:155], v[154:155], v[186:187] op_sel_hi:[1,0]
	v_pk_mul_f32 v[146:147], v[190:191], v[158:159]
	v_mov_b32_e32 v201, v145
	v_pk_mul_f32 v[152:153], v[152:153], v[186:187] op_sel_hi:[1,0]
	v_pk_mul_f32 v[158:159], v[148:149], v[154:155] op_sel:[1,1] op_sel_hi:[0,1]
	v_pk_mul_f32 v[144:145], v[176:177], v[200:201]
	v_pk_fma_f32 v[200:201], v[148:149], v[154:155], v[158:159] op_sel_hi:[1,0,1] neg_lo:[0,0,1] neg_hi:[0,0,1]
	v_pk_fma_f32 v[148:149], v[148:149], v[154:155], v[158:159] op_sel_hi:[1,0,1]
	v_pk_mul_f32 v[154:155], v[150:151], v[152:153] op_sel:[1,1] op_sel_hi:[0,1]
	v_pk_fma_f32 v[158:159], v[150:151], v[152:153], v[154:155] op_sel_hi:[1,0,1] neg_lo:[0,0,1] neg_hi:[0,0,1]
	v_pk_fma_f32 v[150:151], v[150:151], v[152:153], v[154:155] op_sel_hi:[1,0,1]
	v_mov_b32_e32 v201, v149
	v_mov_b32_e32 v159, v151
	v_pk_mul_f32 v[152:153], v[106:107], v[134:135]
	v_pk_mul_f32 v[154:155], v[104:105], v[132:133]
	v_pk_mul_f32 v[150:151], v[190:191], v[158:159]
	v_pk_mul_f32 v[148:149], v[176:177], v[200:201]
	v_pk_mul_f32 v[200:201], v[152:153], v[186:187] op_sel_hi:[1,0]
	v_pk_mul_f32 v[202:203], v[154:155], v[186:187] op_sel_hi:[1,0]
	v_mov_b64_e32 v[152:153], v[240:241]
	v_mov_b64_e32 v[154:155], v[242:243]
	v_mov_b64_e32 v[156:157], v[244:245]
	v_mov_b64_e32 v[158:159], v[246:247]
	v_pk_mul_f32 v[204:205], v[156:157], v[202:203] op_sel:[1,1] op_sel_hi:[0,1]
	v_pk_fma_f32 v[206:207], v[156:157], v[202:203], v[204:205] op_sel_hi:[1,0,1] neg_lo:[0,0,1] neg_hi:[0,0,1]
	v_pk_fma_f32 v[156:157], v[156:157], v[202:203], v[204:205] op_sel_hi:[1,0,1]
	v_pk_mul_f32 v[202:203], v[158:159], v[200:201] op_sel:[1,1] op_sel_hi:[0,1]
	v_pk_fma_f32 v[204:205], v[158:159], v[200:201], v[202:203] op_sel_hi:[1,0,1] neg_lo:[0,0,1] neg_hi:[0,0,1]
	v_pk_fma_f32 v[158:159], v[158:159], v[200:201], v[202:203] op_sel_hi:[1,0,1]
	v_pk_mul_f32 v[200:201], v[78:79], v[130:131]
	v_pk_mul_f32 v[202:203], v[76:77], v[128:129]
	v_pk_mul_f32 v[200:201], v[200:201], v[186:187] op_sel_hi:[1,0]
	v_pk_mul_f32 v[186:187], v[202:203], v[186:187] op_sel_hi:[1,0]
	v_mov_b32_e32 v205, v159
	v_pk_mul_f32 v[202:203], v[152:153], v[186:187] op_sel:[1,1] op_sel_hi:[0,1]
	v_pk_mul_f32 v[158:159], v[190:191], v[204:205]
	v_pk_fma_f32 v[204:205], v[152:153], v[186:187], v[202:203] op_sel_hi:[1,0,1] neg_lo:[0,0,1] neg_hi:[0,0,1]
	v_pk_fma_f32 v[152:153], v[152:153], v[186:187], v[202:203] op_sel_hi:[1,0,1]
	v_pk_mul_f32 v[186:187], v[154:155], v[200:201] op_sel:[1,1] op_sel_hi:[0,1]
	v_pk_fma_f32 v[202:203], v[154:155], v[200:201], v[186:187] op_sel_hi:[1,0,1] neg_lo:[0,0,1] neg_hi:[0,0,1]
	v_pk_fma_f32 v[154:155], v[154:155], v[200:201], v[186:187] op_sel_hi:[1,0,1]
	v_mov_b32_e32 v207, v157
	v_mov_b32_e32 v203, v155
	v_mov_b32_e32 v205, v153
	v_pk_mul_f32 v[156:157], v[176:177], v[206:207]
	v_pk_mul_f32 v[154:155], v[190:191], v[202:203]
	v_pk_mul_f32 v[152:153], v[176:177], v[204:205]
; __device__ __forceinline__ unsigned cvt_pk_bf16(float lo, float hi) { f32x2_c v = {lo, hi}; bf16x2_c b = __builtin_convertvector(v, bf16x2_c); return __builtin_bit_cast(unsigned, b); }
;     __device__ __forceinline__ void operator()(const f32x4 (&acc)[2][2][4][2], const Unit& u, int wr, int wc, int fr, int fq) const {
;     ...
;                 for (int m = 0; m < 4; ++m) { const int row = row0 + ai * HALF + m * 16; bf16_t* rowp = PROJ + (size_t)row * PP + pn * 256 + 64 * wc + 8 * fq;
;                     f32x4 v[2][2];
; #pragma unroll
;                     for (int bj = 0; bj < 2; ++bj)
; #pragma unroll
;                         for (int n = 0; n < 2; ++n) v[bj][n] = acc[ai][bj][m][n];
;                     if (nrm) {
;                         float ss = 0.f;
; #pragma unroll
;                         for (int bj = 0; bj < 2; ++bj)
; #pragma unroll
;                             for (int n = 0; n < 2; ++n) ss += v[bj][n][0] * v[bj][n][0] + v[bj][n][1] * v[bj][n][1] + v[bj][n][2] * v[bj][n][2] + v[bj][n][3] * v[bj][n][3];
;                         ss += __shfl_xor(ss, 16); ss += __shfl_xor(ss, 32);
;                         const float rinv = __builtin_amdgcn_rsqf(ss * (1.f / 64.f) + EPS);
; #pragma unroll
;                         for (int bj = 0; bj < 2; ++bj)
; #pragma unroll
;                             for (int n = 0; n < 2; ++n) { const f32x4 x = v[bj][n] * wv[bj][n] * rinv; const f32x4 cs = *(const f32x4*)(CS + ((size_t)row * 32 + 16 * bj + 4 * fq + 2 * n) * 2);
;                                 f32x4 o; o[0] = x[0] * cs[0] - x[1] * cs[1]; o[1] = x[0] * cs[1] + x[1] * cs[0]; o[2] = x[2] * cs[2] - x[3] * cs[3]; o[3] = x[2] * cs[3] + x[3] * cs[2]; v[bj][n] = o * sc; }
;                     }
; #pragma unroll
;                     for (int bj = 0; bj < 2; ++bj) { u32x4 w; w.x = cvt_pk_bf16(v[bj][0][0], v[bj][0][1]); w.y = cvt_pk_bf16(v[bj][0][2], v[bj][0][3]); w.z = cvt_pk_bf16(v[bj][1][0], v[bj][1][1]); w.w = cvt_pk_bf16(v[bj][1][2], v[bj][1][3]);
;                         *(u32x4*)(rowp + 32 * bj) = w; } }
.LBB0_277:
	v_mov_b64_e32 v[186:187], s[24:25]
	v_mad_i64_i32 v[184:185], s[62:63], v184, s64, v[186:187]
	v_lshl_add_u64 v[184:185], v[184:185], 0, s[56:57]
	v_lshl_add_u64 v[184:185], v[184:185], 0, s[78:79]
	v_lshl_add_u64 v[184:185], v[178:179], 1, v[184:185]
	v_cvt_pk_bf16_f32 v144, v144, v145
	v_cvt_pk_bf16_f32 v145, v146, v147
	v_cvt_pk_bf16_f32 v146, v148, v149
	v_cvt_pk_bf16_f32 v147, v150, v151
	global_store_dwordx4 v[184:185], v[144:147], off
	v_mov_b64_e32 v[150:151], v[66:67]
	s_and_b64 vcc, exec, s[4:5]
	v_cvt_pk_bf16_f32 v144, v156, v157
	v_cvt_pk_bf16_f32 v145, v158, v159
	v_cvt_pk_bf16_f32 v146, v152, v153
	v_cvt_pk_bf16_f32 v147, v154, v155
	global_store_dwordx4 v[184:185], v[144:147], off offset:64
	v_add_u32_e32 v184, 48, v180
	v_mov_b64_e32 v[154:155], v[70:71]
	v_mov_b64_e32 v[158:159], v[94:95]
	v_mov_b64_e32 v[146:147], v[102:103]
	v_ashrrev_i32_e32 v185, 31, v184
	v_mov_b64_e32 v[152:153], v[68:69]
	v_mov_b64_e32 v[156:157], v[92:93]
	v_mov_b64_e32 v[148:149], v[64:65]
	v_mov_b64_e32 v[144:145], v[100:101]
	s_cbranch_vccnz .LBB0_279
	v_mov_b32_e32 v146, v101
	v_mov_b32_e32 v147, v65
	v_mov_b32_e32 v144, v100
	v_mov_b32_e32 v145, v64
	v_pk_mul_f32 v[146:147], v[146:147], v[146:147]
	v_mov_b32_e32 v148, v93
	v_pk_fma_f32 v[144:145], v[144:145], v[144:145], v[146:147]
	v_mov_b32_e32 v146, v102
	v_mov_b32_e32 v147, v66
	v_pk_fma_f32 v[144:145], v[146:147], v[146:147], v[144:145]
	v_mov_b32_e32 v146, v103
	v_mov_b32_e32 v147, v67
	v_mov_b32_e32 v149, v69
	v_pk_fma_f32 v[144:145], v[146:147], v[146:147], v[144:145]
	v_mov_b32_e32 v146, v92
	v_mov_b32_e32 v147, v68
	v_pk_mul_f32 v[148:149], v[148:149], v[148:149]
	v_add_f32_e32 v144, v144, v145
	v_pk_fma_f32 v[146:147], v[146:147], v[146:147], v[148:149]
	v_mov_b32_e32 v148, v94
	v_mov_b32_e32 v149, v70
	v_pk_fma_f32 v[146:147], v[148:149], v[148:149], v[146:147]
	v_mov_b32_e32 v148, v95
	v_mov_b32_e32 v149, v71
	v_pk_fma_f32 v[146:147], v[148:149], v[148:149], v[146:147]
	v_mov_b32_e32 v190, v176
	v_add_f32_e32 v144, v144, v146
	v_add_f32_e32 v144, v144, v147
	ds_bpermute_b32 v145, v196, v144
	v_pk_mul_f32 v[146:147], v[100:101], v[140:141]
	v_mov_b32_e32 v191, v176
	s_waitcnt lgkmcnt(0)
	v_add_f32_e32 v144, v144, v145
	ds_bpermute_b32 v145, v197, v144
	s_waitcnt lgkmcnt(0)
	v_add_f32_e32 v144, v144, v145
	v_fmamk_f32 v144, v144, 0x3c800000, v253
	v_rsq_f32_e32 v186, v144
	v_pk_mul_f32 v[144:145], v[102:103], v[142:143]
	v_pk_mul_f32 v[154:155], v[146:147], v[186:187] op_sel_hi:[1,0]
	v_pk_mul_f32 v[152:153], v[144:145], v[186:187] op_sel_hi:[1,0]
	v_lshlrev_b64 v[144:145], 8, v[184:185]
	v_lshl_add_u64 v[144:145], s[22:23], 0, v[144:145]
	v_lshl_add_u64 v[156:157], v[182:183], 3, v[144:145]
	global_load_dwordx4 v[148:151], v[156:157], off offset:16
	global_load_dwordx4 v[144:147], v[156:157], off
	global_load_dwordx4 v[240:243], v[156:157], off offset:144
	global_load_dwordx4 v[244:247], v[156:157], off offset:128
	s_waitcnt vmcnt(0)
	v_pk_mul_f32 v[158:159], v[144:145], v[154:155] op_sel:[1,1] op_sel_hi:[0,1]
	v_pk_fma_f32 v[200:201], v[144:145], v[154:155], v[158:159] op_sel_hi:[1,0,1] neg_lo:[0,0,1] neg_hi:[0,0,1]
	v_pk_fma_f32 v[144:145], v[144:145], v[154:155], v[158:159] op_sel_hi:[1,0,1]
	v_pk_mul_f32 v[154:155], v[146:147], v[152:153] op_sel:[1,1] op_sel_hi:[0,1]
	v_pk_fma_f32 v[158:159], v[146:147], v[152:153], v[154:155] op_sel_hi:[1,0,1] neg_lo:[0,0,1] neg_hi:[0,0,1]
	v_pk_fma_f32 v[146:147], v[146:147], v[152:153], v[154:155] op_sel_hi:[1,0,1]
	v_pk_mul_f32 v[154:155], v[64:65], v[136:137]
	v_mov_b32_e32 v159, v147
	v_pk_mul_f32 v[152:153], v[66:67], v[138:139]
	v_pk_mul_f32 v[154:155], v[154:155], v[186:187] op_sel_hi:[1,0]
	v_pk_mul_f32 v[146:147], v[190:191], v[158:159]
	v_mov_b32_e32 v201, v145
	v_pk_mul_f32 v[152:153], v[152:153], v[186:187] op_sel_hi:[1,0]
	v_pk_mul_f32 v[158:159], v[148:149], v[154:155] op_sel:[1,1] op_sel_hi:[0,1]
	v_pk_mul_f32 v[144:145], v[176:177], v[200:201]
	v_pk_fma_f32 v[200:201], v[148:149], v[154:155], v[158:159] op_sel_hi:[1,0,1] neg_lo:[0,0,1] neg_hi:[0,0,1]
	v_pk_fma_f32 v[148:149], v[148:149], v[154:155], v[158:159] op_sel_hi:[1,0,1]
	v_pk_mul_f32 v[154:155], v[150:151], v[152:153] op_sel:[1,1] op_sel_hi:[0,1]
	v_pk_fma_f32 v[158:159], v[150:151], v[152:153], v[154:155] op_sel_hi:[1,0,1] neg_lo:[0,0,1] neg_hi:[0,0,1]
	v_pk_fma_f32 v[150:151], v[150:151], v[152:153], v[154:155] op_sel_hi:[1,0,1]
	v_mov_b32_e32 v201, v149
	v_mov_b32_e32 v159, v151
	v_pk_mul_f32 v[152:153], v[94:95], v[134:135]
	v_pk_mul_f32 v[154:155], v[92:93], v[132:133]
	v_pk_mul_f32 v[150:151], v[190:191], v[158:159]
	v_pk_mul_f32 v[148:149], v[176:177], v[200:201]
	v_pk_mul_f32 v[200:201], v[152:153], v[186:187] op_sel_hi:[1,0]
	v_pk_mul_f32 v[202:203], v[154:155], v[186:187] op_sel_hi:[1,0]
	v_mov_b64_e32 v[152:153], v[240:241]
	v_mov_b64_e32 v[154:155], v[242:243]
	v_mov_b64_e32 v[156:157], v[244:245]
	v_mov_b64_e32 v[158:159], v[246:247]
	v_pk_mul_f32 v[204:205], v[156:157], v[202:203] op_sel:[1,1] op_sel_hi:[0,1]
	v_pk_fma_f32 v[206:207], v[156:157], v[202:203], v[204:205] op_sel_hi:[1,0,1] neg_lo:[0,0,1] neg_hi:[0,0,1]
	v_pk_fma_f32 v[156:157], v[156:157], v[202:203], v[204:205] op_sel_hi:[1,0,1]
	v_pk_mul_f32 v[202:203], v[158:159], v[200:201] op_sel:[1,1] op_sel_hi:[0,1]
	v_pk_fma_f32 v[204:205], v[158:159], v[200:201], v[202:203] op_sel_hi:[1,0,1] neg_lo:[0,0,1] neg_hi:[0,0,1]
	v_pk_fma_f32 v[158:159], v[158:159], v[200:201], v[202:203] op_sel_hi:[1,0,1]
	v_pk_mul_f32 v[200:201], v[70:71], v[130:131]
	v_pk_mul_f32 v[202:203], v[68:69], v[128:129]
	v_pk_mul_f32 v[200:201], v[200:201], v[186:187] op_sel_hi:[1,0]
	v_pk_mul_f32 v[186:187], v[202:203], v[186:187] op_sel_hi:[1,0]
	v_mov_b32_e32 v205, v159
	v_pk_mul_f32 v[202:203], v[152:153], v[186:187] op_sel:[1,1] op_sel_hi:[0,1]
	v_pk_mul_f32 v[158:159], v[190:191], v[204:205]
	v_pk_fma_f32 v[204:205], v[152:153], v[186:187], v[202:203] op_sel_hi:[1,0,1] neg_lo:[0,0,1] neg_hi:[0,0,1]
	v_pk_fma_f32 v[152:153], v[152:153], v[186:187], v[202:203] op_sel_hi:[1,0,1]
	v_pk_mul_f32 v[186:187], v[154:155], v[200:201] op_sel:[1,1] op_sel_hi:[0,1]
	v_pk_fma_f32 v[202:203], v[154:155], v[200:201], v[186:187] op_sel_hi:[1,0,1] neg_lo:[0,0,1] neg_hi:[0,0,1]
	v_pk_fma_f32 v[154:155], v[154:155], v[200:201], v[186:187] op_sel_hi:[1,0,1]
	v_mov_b32_e32 v207, v157
	v_mov_b32_e32 v203, v155
	v_mov_b32_e32 v205, v153
	v_pk_mul_f32 v[156:157], v[176:177], v[206:207]
	v_pk_mul_f32 v[154:155], v[190:191], v[202:203]
	v_pk_mul_f32 v[152:153], v[176:177], v[204:205]
; __device__ __forceinline__ unsigned cvt_pk_bf16(float lo, float hi) { f32x2_c v = {lo, hi}; bf16x2_c b = __builtin_convertvector(v, bf16x2_c); return __builtin_bit_cast(unsigned, b); }
;     __device__ __forceinline__ void operator()(const f32x4 (&acc)[2][2][4][2], const Unit& u, int wr, int wc, int fr, int fq) const {
;     ...
;                 for (int m = 0; m < 4; ++m) { const int row = row0 + ai * HALF + m * 16; bf16_t* rowp = PROJ + (size_t)row * PP + pn * 256 + 64 * wc + 8 * fq;
;                     f32x4 v[2][2];
; #pragma unroll
;                     for (int bj = 0; bj < 2; ++bj)
; #pragma unroll
;                         for (int n = 0; n < 2; ++n) v[bj][n] = acc[ai][bj][m][n];
;                     if (nrm) {
;                         float ss = 0.f;
; #pragma unroll
;                         for (int bj = 0; bj < 2; ++bj)
; #pragma unroll
;                             for (int n = 0; n < 2; ++n) ss += v[bj][n][0] * v[bj][n][0] + v[bj][n][1] * v[bj][n][1] + v[bj][n][2] * v[bj][n][2] + v[bj][n][3] * v[bj][n][3];
;                         ss += __shfl_xor(ss, 16); ss += __shfl_xor(ss, 32);
;                         const float rinv = __builtin_amdgcn_rsqf(ss * (1.f / 64.f) + EPS);
; #pragma unroll
;                         for (int bj = 0; bj < 2; ++bj)
; #pragma unroll
;                             for (int n = 0; n < 2; ++n) { const f32x4 x = v[bj][n] * wv[bj][n] * rinv; const f32x4 cs = *(const f32x4*)(CS + ((size_t)row * 32 + 16 * bj + 4 * fq + 2 * n) * 2);
;                                 f32x4 o; o[0] = x[0] * cs[0] - x[1] * cs[1]; o[1] = x[0] * cs[1] + x[1] * cs[0]; o[2] = x[2] * cs[2] - x[3] * cs[3]; o[3] = x[2] * cs[3] + x[3] * cs[2]; v[bj][n] = o * sc; }
;                     }
; #pragma unroll
;                     for (int bj = 0; bj < 2; ++bj) { u32x4 w; w.x = cvt_pk_bf16(v[bj][0][0], v[bj][0][1]); w.y = cvt_pk_bf16(v[bj][0][2], v[bj][0][3]); w.z = cvt_pk_bf16(v[bj][1][0], v[bj][1][1]); w.w = cvt_pk_bf16(v[bj][1][2], v[bj][1][3]);
;                         *(u32x4*)(rowp + 32 * bj) = w; } }
.LBB0_279:
	v_mov_b64_e32 v[186:187], s[24:25]
	v_mad_i64_i32 v[184:185], s[62:63], v184, s64, v[186:187]
	s_mov_b32 s57, s79
	v_lshl_add_u64 v[184:185], v[184:185], 0, s[56:57]
	v_lshl_add_u64 v[184:185], v[184:185], 0, s[78:79]
	v_lshl_add_u64 v[184:185], v[178:179], 1, v[184:185]
	v_cvt_pk_bf16_f32 v144, v144, v145
	v_cvt_pk_bf16_f32 v145, v146, v147
	v_cvt_pk_bf16_f32 v146, v148, v149
	v_cvt_pk_bf16_f32 v147, v150, v151
	global_store_dwordx4 v[184:185], v[144:147], off
	v_mov_b64_e32 v[150:151], v[38:39]
	s_and_b64 vcc, exec, s[4:5]
	v_cvt_pk_bf16_f32 v144, v156, v157
	v_cvt_pk_bf16_f32 v145, v158, v159
	v_cvt_pk_bf16_f32 v146, v152, v153
	v_cvt_pk_bf16_f32 v147, v154, v155
	global_store_dwordx4 v[184:185], v[144:147], off offset:64
	v_add_u32_e32 v184, 0x80, v180
	v_mov_b64_e32 v[154:155], v[46:47]
	v_mov_b64_e32 v[158:159], v[58:59]
	v_mov_b64_e32 v[146:147], v[62:63]
	v_ashrrev_i32_e32 v185, 31, v184
	v_mov_b64_e32 v[152:153], v[44:45]
	v_mov_b64_e32 v[156:157], v[56:57]
	v_mov_b64_e32 v[148:149], v[36:37]
	v_mov_b64_e32 v[144:145], v[60:61]
	s_cbranch_vccnz .LBB0_281
	v_mov_b32_e32 v146, v61
	v_mov_b32_e32 v147, v37
	v_mov_b32_e32 v144, v60
	v_mov_b32_e32 v145, v36
	v_pk_mul_f32 v[146:147], v[146:147], v[146:147]
	v_mov_b32_e32 v148, v57
	v_pk_fma_f32 v[144:145], v[144:145], v[144:145], v[146:147]
	v_mov_b32_e32 v146, v62
	v_mov_b32_e32 v147, v38
	v_pk_fma_f32 v[144:145], v[146:147], v[146:147], v[144:145]
	v_mov_b32_e32 v146, v63
	v_mov_b32_e32 v147, v39
	v_mov_b32_e32 v149, v45
	v_pk_fma_f32 v[144:145], v[146:147], v[146:147], v[144:145]
	v_mov_b32_e32 v146, v56
	v_mov_b32_e32 v147, v44
	v_pk_mul_f32 v[148:149], v[148:149], v[148:149]
	v_add_f32_e32 v144, v144, v145
	v_pk_fma_f32 v[146:147], v[146:147], v[146:147], v[148:149]
	v_mov_b32_e32 v148, v58
	v_mov_b32_e32 v149, v46
	v_pk_fma_f32 v[146:147], v[148:149], v[148:149], v[146:147]
	v_mov_b32_e32 v148, v59
	v_mov_b32_e32 v149, v47
	v_pk_fma_f32 v[146:147], v[148:149], v[148:149], v[146:147]
	v_mov_b32_e32 v190, v176
	v_add_f32_e32 v144, v144, v146
	v_add_f32_e32 v144, v144, v147
	ds_bpermute_b32 v145, v196, v144
	v_pk_mul_f32 v[146:147], v[60:61], v[140:141]
	v_mov_b32_e32 v191, v176
	s_waitcnt lgkmcnt(0)
	v_add_f32_e32 v144, v144, v145
	ds_bpermute_b32 v145, v197, v144
	s_waitcnt lgkmcnt(0)
	v_add_f32_e32 v144, v144, v145
	v_fmamk_f32 v144, v144, 0x3c800000, v253
	v_rsq_f32_e32 v186, v144
	v_pk_mul_f32 v[144:145], v[62:63], v[142:143]
	v_pk_mul_f32 v[154:155], v[146:147], v[186:187] op_sel_hi:[1,0]
	v_pk_mul_f32 v[152:153], v[144:145], v[186:187] op_sel_hi:[1,0]
	v_lshlrev_b64 v[144:145], 8, v[184:185]
	v_lshl_add_u64 v[144:145], s[22:23], 0, v[144:145]
	v_lshl_add_u64 v[156:157], v[182:183], 3, v[144:145]
	global_load_dwordx4 v[148:151], v[156:157], off offset:16
	global_load_dwordx4 v[144:147], v[156:157], off
	global_load_dwordx4 v[240:243], v[156:157], off offset:144
	global_load_dwordx4 v[244:247], v[156:157], off offset:128
	s_waitcnt vmcnt(0)
	v_pk_mul_f32 v[158:159], v[144:145], v[154:155] op_sel:[1,1] op_sel_hi:[0,1]
	v_pk_fma_f32 v[200:201], v[144:145], v[154:155], v[158:159] op_sel_hi:[1,0,1] neg_lo:[0,0,1] neg_hi:[0,0,1]
	v_pk_fma_f32 v[144:145], v[144:145], v[154:155], v[158:159] op_sel_hi:[1,0,1]
	v_pk_mul_f32 v[154:155], v[146:147], v[152:153] op_sel:[1,1] op_sel_hi:[0,1]
	v_pk_fma_f32 v[158:159], v[146:147], v[152:153], v[154:155] op_sel_hi:[1,0,1] neg_lo:[0,0,1] neg_hi:[0,0,1]
	v_pk_fma_f32 v[146:147], v[146:147], v[152:153], v[154:155] op_sel_hi:[1,0,1]
	v_pk_mul_f32 v[154:155], v[36:37], v[136:137]
	v_mov_b32_e32 v159, v147
	v_pk_mul_f32 v[152:153], v[38:39], v[138:139]
	v_pk_mul_f32 v[154:155], v[154:155], v[186:187] op_sel_hi:[1,0]
	v_pk_mul_f32 v[146:147], v[190:191], v[158:159]
	v_mov_b32_e32 v201, v145
	v_pk_mul_f32 v[152:153], v[152:153], v[186:187] op_sel_hi:[1,0]
	v_pk_mul_f32 v[158:159], v[148:149], v[154:155] op_sel:[1,1] op_sel_hi:[0,1]
	v_pk_mul_f32 v[144:145], v[176:177], v[200:201]
	v_pk_fma_f32 v[200:201], v[148:149], v[154:155], v[158:159] op_sel_hi:[1,0,1] neg_lo:[0,0,1] neg_hi:[0,0,1]
	v_pk_fma_f32 v[148:149], v[148:149], v[154:155], v[158:159] op_sel_hi:[1,0,1]
	v_pk_mul_f32 v[154:155], v[150:151], v[152:153] op_sel:[1,1] op_sel_hi:[0,1]
	v_pk_fma_f32 v[158:159], v[150:151], v[152:153], v[154:155] op_sel_hi:[1,0,1] neg_lo:[0,0,1] neg_hi:[0,0,1]
	v_pk_fma_f32 v[150:151], v[150:151], v[152:153], v[154:155] op_sel_hi:[1,0,1]
	v_mov_b32_e32 v201, v149
	v_mov_b32_e32 v159, v151
	v_pk_mul_f32 v[152:153], v[58:59], v[134:135]
	v_pk_mul_f32 v[154:155], v[56:57], v[132:133]
	v_pk_mul_f32 v[150:151], v[190:191], v[158:159]
	v_pk_mul_f32 v[148:149], v[176:177], v[200:201]
	v_pk_mul_f32 v[200:201], v[152:153], v[186:187] op_sel_hi:[1,0]
	v_pk_mul_f32 v[202:203], v[154:155], v[186:187] op_sel_hi:[1,0]
	v_mov_b64_e32 v[152:153], v[240:241]
	v_mov_b64_e32 v[154:155], v[242:243]
	v_mov_b64_e32 v[156:157], v[244:245]
	v_mov_b64_e32 v[158:159], v[246:247]
	v_pk_mul_f32 v[204:205], v[156:157], v[202:203] op_sel:[1,1] op_sel_hi:[0,1]
	v_pk_fma_f32 v[206:207], v[156:157], v[202:203], v[204:205] op_sel_hi:[1,0,1] neg_lo:[0,0,1] neg_hi:[0,0,1]
	v_pk_fma_f32 v[156:157], v[156:157], v[202:203], v[204:205] op_sel_hi:[1,0,1]
	v_pk_mul_f32 v[202:203], v[158:159], v[200:201] op_sel:[1,1] op_sel_hi:[0,1]
	v_pk_fma_f32 v[204:205], v[158:159], v[200:201], v[202:203] op_sel_hi:[1,0,1] neg_lo:[0,0,1] neg_hi:[0,0,1]
	v_pk_fma_f32 v[158:159], v[158:159], v[200:201], v[202:203] op_sel_hi:[1,0,1]
	v_pk_mul_f32 v[200:201], v[46:47], v[130:131]
	v_pk_mul_f32 v[202:203], v[44:45], v[128:129]
	v_pk_mul_f32 v[200:201], v[200:201], v[186:187] op_sel_hi:[1,0]
	v_pk_mul_f32 v[186:187], v[202:203], v[186:187] op_sel_hi:[1,0]
	v_mov_b32_e32 v205, v159
	v_pk_mul_f32 v[202:203], v[152:153], v[186:187] op_sel:[1,1] op_sel_hi:[0,1]
	v_pk_mul_f32 v[158:159], v[190:191], v[204:205]
	v_pk_fma_f32 v[204:205], v[152:153], v[186:187], v[202:203] op_sel_hi:[1,0,1] neg_lo:[0,0,1] neg_hi:[0,0,1]
	v_pk_fma_f32 v[152:153], v[152:153], v[186:187], v[202:203] op_sel_hi:[1,0,1]
	v_pk_mul_f32 v[186:187], v[154:155], v[200:201] op_sel:[1,1] op_sel_hi:[0,1]
	v_pk_fma_f32 v[202:203], v[154:155], v[200:201], v[186:187] op_sel_hi:[1,0,1] neg_lo:[0,0,1] neg_hi:[0,0,1]
	v_pk_fma_f32 v[154:155], v[154:155], v[200:201], v[186:187] op_sel_hi:[1,0,1]
	v_mov_b32_e32 v207, v157
	v_mov_b32_e32 v203, v155
	v_mov_b32_e32 v205, v153
	v_pk_mul_f32 v[156:157], v[176:177], v[206:207]
	v_pk_mul_f32 v[154:155], v[190:191], v[202:203]
	v_pk_mul_f32 v[152:153], v[176:177], v[204:205]
; __device__ __forceinline__ unsigned cvt_pk_bf16(float lo, float hi) { f32x2_c v = {lo, hi}; bf16x2_c b = __builtin_convertvector(v, bf16x2_c); return __builtin_bit_cast(unsigned, b); }
;     __device__ __forceinline__ void operator()(const f32x4 (&acc)[2][2][4][2], const Unit& u, int wr, int wc, int fr, int fq) const {
;     ...
;                 for (int m = 0; m < 4; ++m) { const int row = row0 + ai * HALF + m * 16; bf16_t* rowp = PROJ + (size_t)row * PP + pn * 256 + 64 * wc + 8 * fq;
;                     f32x4 v[2][2];
; #pragma unroll
;                     for (int bj = 0; bj < 2; ++bj)
; #pragma unroll
;                         for (int n = 0; n < 2; ++n) v[bj][n] = acc[ai][bj][m][n];
;                     if (nrm) {
;                         float ss = 0.f;
; #pragma unroll
;                         for (int bj = 0; bj < 2; ++bj)
; #pragma unroll
;                             for (int n = 0; n < 2; ++n) ss += v[bj][n][0] * v[bj][n][0] + v[bj][n][1] * v[bj][n][1] + v[bj][n][2] * v[bj][n][2] + v[bj][n][3] * v[bj][n][3];
;                         ss += __shfl_xor(ss, 16); ss += __shfl_xor(ss, 32);
;                         const float rinv = __builtin_amdgcn_rsqf(ss * (1.f / 64.f) + EPS);
; #pragma unroll
;                         for (int bj = 0; bj < 2; ++bj)
; #pragma unroll
;                             for (int n = 0; n < 2; ++n) { const f32x4 x = v[bj][n] * wv[bj][n] * rinv; const f32x4 cs = *(const f32x4*)(CS + ((size_t)row * 32 + 16 * bj + 4 * fq + 2 * n) * 2);
;                                 f32x4 o; o[0] = x[0] * cs[0] - x[1] * cs[1]; o[1] = x[0] * cs[1] + x[1] * cs[0]; o[2] = x[2] * cs[2] - x[3] * cs[3]; o[3] = x[2] * cs[3] + x[3] * cs[2]; v[bj][n] = o * sc; }
;                     }
; #pragma unroll
;                     for (int bj = 0; bj < 2; ++bj) { u32x4 w; w.x = cvt_pk_bf16(v[bj][0][0], v[bj][0][1]); w.y = cvt_pk_bf16(v[bj][0][2], v[bj][0][3]); w.z = cvt_pk_bf16(v[bj][1][0], v[bj][1][1]); w.w = cvt_pk_bf16(v[bj][1][2], v[bj][1][3]);
;                         *(u32x4*)(rowp + 32 * bj) = w; } }
.LBB0_281:
	v_mov_b64_e32 v[186:187], s[24:25]
	v_mad_i64_i32 v[184:185], s[62:63], v184, s64, v[186:187]
	v_lshl_add_u64 v[184:185], v[184:185], 0, s[56:57]
	v_lshl_add_u64 v[184:185], v[184:185], 0, s[78:79]
	v_lshl_add_u64 v[184:185], v[178:179], 1, v[184:185]
	v_cvt_pk_bf16_f32 v144, v144, v145
	v_cvt_pk_bf16_f32 v145, v146, v147
	v_cvt_pk_bf16_f32 v146, v148, v149
	v_cvt_pk_bf16_f32 v147, v150, v151
	global_store_dwordx4 v[184:185], v[144:147], off
	v_mov_b64_e32 v[150:151], v[26:27]
	s_and_b64 vcc, exec, s[4:5]
	v_cvt_pk_bf16_f32 v144, v156, v157
	v_cvt_pk_bf16_f32 v145, v158, v159
	v_cvt_pk_bf16_f32 v146, v152, v153
	v_cvt_pk_bf16_f32 v147, v154, v155
	global_store_dwordx4 v[184:185], v[144:147], off offset:64
	v_add_u32_e32 v184, 0x90, v180
	v_mov_b64_e32 v[154:155], v[34:35]
	v_mov_b64_e32 v[158:159], v[50:51]
	v_mov_b64_e32 v[146:147], v[54:55]
	v_ashrrev_i32_e32 v185, 31, v184
	v_mov_b64_e32 v[152:153], v[32:33]
	v_mov_b64_e32 v[156:157], v[48:49]
	v_mov_b64_e32 v[148:149], v[24:25]
	v_mov_b64_e32 v[144:145], v[52:53]
	s_cbranch_vccnz .LBB0_283
	v_mov_b32_e32 v146, v53
	v_mov_b32_e32 v147, v25
	v_mov_b32_e32 v144, v52
	v_mov_b32_e32 v145, v24
	v_pk_mul_f32 v[146:147], v[146:147], v[146:147]
	v_mov_b32_e32 v148, v49
	v_pk_fma_f32 v[144:145], v[144:145], v[144:145], v[146:147]
	v_mov_b32_e32 v146, v54
	v_mov_b32_e32 v147, v26
	v_pk_fma_f32 v[144:145], v[146:147], v[146:147], v[144:145]
	v_mov_b32_e32 v146, v55
	v_mov_b32_e32 v147, v27
	v_mov_b32_e32 v149, v33
	v_pk_fma_f32 v[144:145], v[146:147], v[146:147], v[144:145]
	v_mov_b32_e32 v146, v48
	v_mov_b32_e32 v147, v32
	v_pk_mul_f32 v[148:149], v[148:149], v[148:149]
	v_add_f32_e32 v144, v144, v145
	v_pk_fma_f32 v[146:147], v[146:147], v[146:147], v[148:149]
	v_mov_b32_e32 v148, v50
	v_mov_b32_e32 v149, v34
	v_pk_fma_f32 v[146:147], v[148:149], v[148:149], v[146:147]
	v_mov_b32_e32 v148, v51
	v_mov_b32_e32 v149, v35
	v_pk_fma_f32 v[146:147], v[148:149], v[148:149], v[146:147]
	v_mov_b32_e32 v190, v176
	v_add_f32_e32 v144, v144, v146
	v_add_f32_e32 v144, v144, v147
	ds_bpermute_b32 v145, v196, v144
	v_pk_mul_f32 v[146:147], v[52:53], v[140:141]
	v_mov_b32_e32 v191, v176
	s_waitcnt lgkmcnt(0)
	v_add_f32_e32 v144, v144, v145
	ds_bpermute_b32 v145, v197, v144
	s_waitcnt lgkmcnt(0)
	v_add_f32_e32 v144, v144, v145
	v_fmamk_f32 v144, v144, 0x3c800000, v253
	v_rsq_f32_e32 v186, v144
	v_pk_mul_f32 v[144:145], v[54:55], v[142:143]
	v_pk_mul_f32 v[154:155], v[146:147], v[186:187] op_sel_hi:[1,0]
	v_pk_mul_f32 v[152:153], v[144:145], v[186:187] op_sel_hi:[1,0]
	v_lshlrev_b64 v[144:145], 8, v[184:185]
	v_lshl_add_u64 v[144:145], s[22:23], 0, v[144:145]
	v_lshl_add_u64 v[156:157], v[182:183], 3, v[144:145]
	global_load_dwordx4 v[148:151], v[156:157], off offset:16
	global_load_dwordx4 v[144:147], v[156:157], off
	global_load_dwordx4 v[240:243], v[156:157], off offset:144
	global_load_dwordx4 v[244:247], v[156:157], off offset:128
	s_waitcnt vmcnt(0)
	v_pk_mul_f32 v[158:159], v[144:145], v[154:155] op_sel:[1,1] op_sel_hi:[0,1]
	v_pk_fma_f32 v[200:201], v[144:145], v[154:155], v[158:159] op_sel_hi:[1,0,1] neg_lo:[0,0,1] neg_hi:[0,0,1]
	v_pk_fma_f32 v[144:145], v[144:145], v[154:155], v[158:159] op_sel_hi:[1,0,1]
	v_pk_mul_f32 v[154:155], v[146:147], v[152:153] op_sel:[1,1] op_sel_hi:[0,1]
	v_pk_fma_f32 v[158:159], v[146:147], v[152:153], v[154:155] op_sel_hi:[1,0,1] neg_lo:[0,0,1] neg_hi:[0,0,1]
	v_pk_fma_f32 v[146:147], v[146:147], v[152:153], v[154:155] op_sel_hi:[1,0,1]
	v_pk_mul_f32 v[154:155], v[24:25], v[136:137]
	v_mov_b32_e32 v159, v147
	v_pk_mul_f32 v[152:153], v[26:27], v[138:139]
	v_pk_mul_f32 v[154:155], v[154:155], v[186:187] op_sel_hi:[1,0]
	v_pk_mul_f32 v[146:147], v[190:191], v[158:159]
	v_mov_b32_e32 v201, v145
	v_pk_mul_f32 v[152:153], v[152:153], v[186:187] op_sel_hi:[1,0]
	v_pk_mul_f32 v[158:159], v[148:149], v[154:155] op_sel:[1,1] op_sel_hi:[0,1]
	v_pk_mul_f32 v[144:145], v[176:177], v[200:201]
	v_pk_fma_f32 v[200:201], v[148:149], v[154:155], v[158:159] op_sel_hi:[1,0,1] neg_lo:[0,0,1] neg_hi:[0,0,1]
	v_pk_fma_f32 v[148:149], v[148:149], v[154:155], v[158:159] op_sel_hi:[1,0,1]
	v_pk_mul_f32 v[154:155], v[150:151], v[152:153] op_sel:[1,1] op_sel_hi:[0,1]
	v_pk_fma_f32 v[158:159], v[150:151], v[152:153], v[154:155] op_sel_hi:[1,0,1] neg_lo:[0,0,1] neg_hi:[0,0,1]
	v_pk_fma_f32 v[150:151], v[150:151], v[152:153], v[154:155] op_sel_hi:[1,0,1]
	v_mov_b32_e32 v201, v149
	v_mov_b32_e32 v159, v151
	v_pk_mul_f32 v[152:153], v[50:51], v[134:135]
	v_pk_mul_f32 v[154:155], v[48:49], v[132:133]
	v_pk_mul_f32 v[150:151], v[190:191], v[158:159]
	v_pk_mul_f32 v[148:149], v[176:177], v[200:201]
	v_pk_mul_f32 v[200:201], v[152:153], v[186:187] op_sel_hi:[1,0]
	v_pk_mul_f32 v[202:203], v[154:155], v[186:187] op_sel_hi:[1,0]
	v_mov_b64_e32 v[152:153], v[240:241]
	v_mov_b64_e32 v[154:155], v[242:243]
	v_mov_b64_e32 v[156:157], v[244:245]
	v_mov_b64_e32 v[158:159], v[246:247]
	v_pk_mul_f32 v[204:205], v[156:157], v[202:203] op_sel:[1,1] op_sel_hi:[0,1]
	v_pk_fma_f32 v[206:207], v[156:157], v[202:203], v[204:205] op_sel_hi:[1,0,1] neg_lo:[0,0,1] neg_hi:[0,0,1]
	v_pk_fma_f32 v[156:157], v[156:157], v[202:203], v[204:205] op_sel_hi:[1,0,1]
	v_pk_mul_f32 v[202:203], v[158:159], v[200:201] op_sel:[1,1] op_sel_hi:[0,1]
	v_pk_fma_f32 v[204:205], v[158:159], v[200:201], v[202:203] op_sel_hi:[1,0,1] neg_lo:[0,0,1] neg_hi:[0,0,1]
	v_pk_fma_f32 v[158:159], v[158:159], v[200:201], v[202:203] op_sel_hi:[1,0,1]
	v_pk_mul_f32 v[200:201], v[34:35], v[130:131]
	v_pk_mul_f32 v[202:203], v[32:33], v[128:129]
	v_pk_mul_f32 v[200:201], v[200:201], v[186:187] op_sel_hi:[1,0]
	v_pk_mul_f32 v[186:187], v[202:203], v[186:187] op_sel_hi:[1,0]
	v_mov_b32_e32 v205, v159
	v_pk_mul_f32 v[202:203], v[152:153], v[186:187] op_sel:[1,1] op_sel_hi:[0,1]
	v_pk_mul_f32 v[158:159], v[190:191], v[204:205]
	v_pk_fma_f32 v[204:205], v[152:153], v[186:187], v[202:203] op_sel_hi:[1,0,1] neg_lo:[0,0,1] neg_hi:[0,0,1]
	v_pk_fma_f32 v[152:153], v[152:153], v[186:187], v[202:203] op_sel_hi:[1,0,1]
	v_pk_mul_f32 v[186:187], v[154:155], v[200:201] op_sel:[1,1] op_sel_hi:[0,1]
	v_pk_fma_f32 v[202:203], v[154:155], v[200:201], v[186:187] op_sel_hi:[1,0,1] neg_lo:[0,0,1] neg_hi:[0,0,1]
	v_pk_fma_f32 v[154:155], v[154:155], v[200:201], v[186:187] op_sel_hi:[1,0,1]
	v_mov_b32_e32 v207, v157
	v_mov_b32_e32 v203, v155
	v_mov_b32_e32 v205, v153
	v_pk_mul_f32 v[156:157], v[176:177], v[206:207]
	v_pk_mul_f32 v[154:155], v[190:191], v[202:203]
	v_pk_mul_f32 v[152:153], v[176:177], v[204:205]
; __device__ __forceinline__ unsigned cvt_pk_bf16(float lo, float hi) { f32x2_c v = {lo, hi}; bf16x2_c b = __builtin_convertvector(v, bf16x2_c); return __builtin_bit_cast(unsigned, b); }
;     __device__ __forceinline__ void operator()(const f32x4 (&acc)[2][2][4][2], const Unit& u, int wr, int wc, int fr, int fq) const {
;     ...
;                 for (int m = 0; m < 4; ++m) { const int row = row0 + ai * HALF + m * 16; bf16_t* rowp = PROJ + (size_t)row * PP + pn * 256 + 64 * wc + 8 * fq;
;                     f32x4 v[2][2];
; #pragma unroll
;                     for (int bj = 0; bj < 2; ++bj)
; #pragma unroll
;                         for (int n = 0; n < 2; ++n) v[bj][n] = acc[ai][bj][m][n];
;                     if (nrm) {
;                         float ss = 0.f;
; #pragma unroll
;                         for (int bj = 0; bj < 2; ++bj)
; #pragma unroll
;                             for (int n = 0; n < 2; ++n) ss += v[bj][n][0] * v[bj][n][0] + v[bj][n][1] * v[bj][n][1] + v[bj][n][2] * v[bj][n][2] + v[bj][n][3] * v[bj][n][3];
;                         ss += __shfl_xor(ss, 16); ss += __shfl_xor(ss, 32);
;                         const float rinv = __builtin_amdgcn_rsqf(ss * (1.f / 64.f) + EPS);
; #pragma unroll
;                         for (int bj = 0; bj < 2; ++bj)
; #pragma unroll
;                             for (int n = 0; n < 2; ++n) { const f32x4 x = v[bj][n] * wv[bj][n] * rinv; const f32x4 cs = *(const f32x4*)(CS + ((size_t)row * 32 + 16 * bj + 4 * fq + 2 * n) * 2);
;                                 f32x4 o; o[0] = x[0] * cs[0] - x[1] * cs[1]; o[1] = x[0] * cs[1] + x[1] * cs[0]; o[2] = x[2] * cs[2] - x[3] * cs[3]; o[3] = x[2] * cs[3] + x[3] * cs[2]; v[bj][n] = o * sc; }
;                     }
; #pragma unroll
;                     for (int bj = 0; bj < 2; ++bj) { u32x4 w; w.x = cvt_pk_bf16(v[bj][0][0], v[bj][0][1]); w.y = cvt_pk_bf16(v[bj][0][2], v[bj][0][3]); w.z = cvt_pk_bf16(v[bj][1][0], v[bj][1][1]); w.w = cvt_pk_bf16(v[bj][1][2], v[bj][1][3]);
;                         *(u32x4*)(rowp + 32 * bj) = w; } }
.LBB0_283:
	v_mov_b64_e32 v[186:187], s[24:25]
	v_mad_i64_i32 v[184:185], s[62:63], v184, s64, v[186:187]
	s_mov_b32 s57, s79
	v_lshl_add_u64 v[184:185], v[184:185], 0, s[56:57]
	v_lshl_add_u64 v[184:185], v[184:185], 0, s[78:79]
	v_lshl_add_u64 v[184:185], v[178:179], 1, v[184:185]
	v_cvt_pk_bf16_f32 v144, v144, v145
	v_cvt_pk_bf16_f32 v145, v146, v147
	v_cvt_pk_bf16_f32 v146, v148, v149
	v_cvt_pk_bf16_f32 v147, v150, v151
	global_store_dwordx4 v[184:185], v[144:147], off
	v_mov_b64_e32 v[150:151], v[14:15]
	s_and_b64 vcc, exec, s[4:5]
	v_cvt_pk_bf16_f32 v144, v156, v157
	v_cvt_pk_bf16_f32 v145, v158, v159
	v_cvt_pk_bf16_f32 v146, v152, v153
	v_cvt_pk_bf16_f32 v147, v154, v155
	global_store_dwordx4 v[184:185], v[144:147], off offset:64
	v_add_u32_e32 v184, 0xa0, v180
	v_mov_b64_e32 v[154:155], v[18:19]
	v_mov_b64_e32 v[158:159], v[30:31]
	v_mov_b64_e32 v[146:147], v[42:43]
	v_ashrrev_i32_e32 v185, 31, v184
	v_mov_b64_e32 v[152:153], v[16:17]
	v_mov_b64_e32 v[156:157], v[28:29]
	v_mov_b64_e32 v[148:149], v[12:13]
	v_mov_b64_e32 v[144:145], v[40:41]
	s_cbranch_vccnz .LBB0_285
	v_mov_b32_e32 v146, v41
	v_mov_b32_e32 v147, v13
	v_mov_b32_e32 v144, v40
	v_mov_b32_e32 v145, v12
	v_pk_mul_f32 v[146:147], v[146:147], v[146:147]
	v_mov_b32_e32 v148, v29
	v_pk_fma_f32 v[144:145], v[144:145], v[144:145], v[146:147]
	v_mov_b32_e32 v146, v42
	v_mov_b32_e32 v147, v14
	v_pk_fma_f32 v[144:145], v[146:147], v[146:147], v[144:145]
	v_mov_b32_e32 v146, v43
	v_mov_b32_e32 v147, v15
	v_mov_b32_e32 v149, v17
	v_pk_fma_f32 v[144:145], v[146:147], v[146:147], v[144:145]
	v_mov_b32_e32 v146, v28
	v_mov_b32_e32 v147, v16
	v_pk_mul_f32 v[148:149], v[148:149], v[148:149]
	v_add_f32_e32 v144, v144, v145
	v_pk_fma_f32 v[146:147], v[146:147], v[146:147], v[148:149]
	v_mov_b32_e32 v148, v30
	v_mov_b32_e32 v149, v18
	v_pk_fma_f32 v[146:147], v[148:149], v[148:149], v[146:147]
	v_mov_b32_e32 v148, v31
	v_mov_b32_e32 v149, v19
	v_pk_fma_f32 v[146:147], v[148:149], v[148:149], v[146:147]
	v_mov_b32_e32 v190, v176
	v_add_f32_e32 v144, v144, v146
	v_add_f32_e32 v144, v144, v147
	ds_bpermute_b32 v145, v196, v144
	v_pk_mul_f32 v[146:147], v[40:41], v[140:141]
	v_mov_b32_e32 v191, v176
	s_waitcnt lgkmcnt(0)
	v_add_f32_e32 v144, v144, v145
	ds_bpermute_b32 v145, v197, v144
	s_waitcnt lgkmcnt(0)
	v_add_f32_e32 v144, v144, v145
	v_fmamk_f32 v144, v144, 0x3c800000, v253
	v_rsq_f32_e32 v186, v144
	v_pk_mul_f32 v[144:145], v[42:43], v[142:143]
	v_pk_mul_f32 v[154:155], v[146:147], v[186:187] op_sel_hi:[1,0]
	v_pk_mul_f32 v[152:153], v[144:145], v[186:187] op_sel_hi:[1,0]
	v_lshlrev_b64 v[144:145], 8, v[184:185]
	v_lshl_add_u64 v[144:145], s[22:23], 0, v[144:145]
	v_lshl_add_u64 v[156:157], v[182:183], 3, v[144:145]
	global_load_dwordx4 v[148:151], v[156:157], off offset:16
	global_load_dwordx4 v[144:147], v[156:157], off
	global_load_dwordx4 v[240:243], v[156:157], off offset:144
	global_load_dwordx4 v[244:247], v[156:157], off offset:128
	s_waitcnt vmcnt(0)
	v_pk_mul_f32 v[158:159], v[144:145], v[154:155] op_sel:[1,1] op_sel_hi:[0,1]
	v_pk_fma_f32 v[200:201], v[144:145], v[154:155], v[158:159] op_sel_hi:[1,0,1] neg_lo:[0,0,1] neg_hi:[0,0,1]
	v_pk_fma_f32 v[144:145], v[144:145], v[154:155], v[158:159] op_sel_hi:[1,0,1]
	v_pk_mul_f32 v[154:155], v[146:147], v[152:153] op_sel:[1,1] op_sel_hi:[0,1]
	v_pk_fma_f32 v[158:159], v[146:147], v[152:153], v[154:155] op_sel_hi:[1,0,1] neg_lo:[0,0,1] neg_hi:[0,0,1]
	v_pk_fma_f32 v[146:147], v[146:147], v[152:153], v[154:155] op_sel_hi:[1,0,1]
	v_pk_mul_f32 v[154:155], v[12:13], v[136:137]
	v_mov_b32_e32 v159, v147
	v_pk_mul_f32 v[152:153], v[14:15], v[138:139]
	v_pk_mul_f32 v[154:155], v[154:155], v[186:187] op_sel_hi:[1,0]
	v_pk_mul_f32 v[146:147], v[190:191], v[158:159]
	v_mov_b32_e32 v201, v145
	v_pk_mul_f32 v[152:153], v[152:153], v[186:187] op_sel_hi:[1,0]
	v_pk_mul_f32 v[158:159], v[148:149], v[154:155] op_sel:[1,1] op_sel_hi:[0,1]
	v_pk_mul_f32 v[144:145], v[176:177], v[200:201]
	v_pk_fma_f32 v[200:201], v[148:149], v[154:155], v[158:159] op_sel_hi:[1,0,1] neg_lo:[0,0,1] neg_hi:[0,0,1]
	v_pk_fma_f32 v[148:149], v[148:149], v[154:155], v[158:159] op_sel_hi:[1,0,1]
	v_pk_mul_f32 v[154:155], v[150:151], v[152:153] op_sel:[1,1] op_sel_hi:[0,1]
	v_pk_fma_f32 v[158:159], v[150:151], v[152:153], v[154:155] op_sel_hi:[1,0,1] neg_lo:[0,0,1] neg_hi:[0,0,1]
	v_pk_fma_f32 v[150:151], v[150:151], v[152:153], v[154:155] op_sel_hi:[1,0,1]
	v_mov_b32_e32 v201, v149
	v_mov_b32_e32 v159, v151
	v_pk_mul_f32 v[152:153], v[30:31], v[134:135]
	v_pk_mul_f32 v[154:155], v[28:29], v[132:133]
	v_pk_mul_f32 v[150:151], v[190:191], v[158:159]
	v_pk_mul_f32 v[148:149], v[176:177], v[200:201]
	v_pk_mul_f32 v[200:201], v[152:153], v[186:187] op_sel_hi:[1,0]
	v_pk_mul_f32 v[202:203], v[154:155], v[186:187] op_sel_hi:[1,0]
	v_mov_b64_e32 v[152:153], v[240:241]
	v_mov_b64_e32 v[154:155], v[242:243]
	v_mov_b64_e32 v[156:157], v[244:245]
	v_mov_b64_e32 v[158:159], v[246:247]
	v_pk_mul_f32 v[204:205], v[156:157], v[202:203] op_sel:[1,1] op_sel_hi:[0,1]
	v_pk_fma_f32 v[206:207], v[156:157], v[202:203], v[204:205] op_sel_hi:[1,0,1] neg_lo:[0,0,1] neg_hi:[0,0,1]
	v_pk_fma_f32 v[156:157], v[156:157], v[202:203], v[204:205] op_sel_hi:[1,0,1]
	v_pk_mul_f32 v[202:203], v[158:159], v[200:201] op_sel:[1,1] op_sel_hi:[0,1]
	v_pk_fma_f32 v[204:205], v[158:159], v[200:201], v[202:203] op_sel_hi:[1,0,1] neg_lo:[0,0,1] neg_hi:[0,0,1]
	v_pk_fma_f32 v[158:159], v[158:159], v[200:201], v[202:203] op_sel_hi:[1,0,1]
	v_pk_mul_f32 v[200:201], v[18:19], v[130:131]
	v_pk_mul_f32 v[202:203], v[16:17], v[128:129]
	v_pk_mul_f32 v[200:201], v[200:201], v[186:187] op_sel_hi:[1,0]
	v_pk_mul_f32 v[186:187], v[202:203], v[186:187] op_sel_hi:[1,0]
	v_mov_b32_e32 v205, v159
	v_pk_mul_f32 v[202:203], v[152:153], v[186:187] op_sel:[1,1] op_sel_hi:[0,1]
	v_pk_mul_f32 v[158:159], v[190:191], v[204:205]
	v_pk_fma_f32 v[204:205], v[152:153], v[186:187], v[202:203] op_sel_hi:[1,0,1] neg_lo:[0,0,1] neg_hi:[0,0,1]
	v_pk_fma_f32 v[152:153], v[152:153], v[186:187], v[202:203] op_sel_hi:[1,0,1]
	v_pk_mul_f32 v[186:187], v[154:155], v[200:201] op_sel:[1,1] op_sel_hi:[0,1]
	v_pk_fma_f32 v[202:203], v[154:155], v[200:201], v[186:187] op_sel_hi:[1,0,1] neg_lo:[0,0,1] neg_hi:[0,0,1]
	v_pk_fma_f32 v[154:155], v[154:155], v[200:201], v[186:187] op_sel_hi:[1,0,1]
	v_mov_b32_e32 v207, v157
	v_mov_b32_e32 v203, v155
	v_mov_b32_e32 v205, v153
	v_pk_mul_f32 v[156:157], v[176:177], v[206:207]
	v_pk_mul_f32 v[154:155], v[190:191], v[202:203]
	v_pk_mul_f32 v[152:153], v[176:177], v[204:205]

; __global__ void __launch_bounds__(NWAVES * 64, 2) mk_fwd(Args args) {
;     ...
;     if (IN(17)) {
;         PHASE_BEGIN
;         for (int m = gw; m < SEQ; m += NGW) {
;             const f32x4* xr = (const f32x4*)(XR + (size_t)m * DMODEL) + lane;
;             f32x4 v[8]; float s = 0.f;
; #pragma unroll
;             for (int j = 0; j < 8; ++j) { v[j] = xr[64 * j]; s += (v[j][0] * v[j][0] + v[j][1] * v[j][1]) + (v[j][2] * v[j][2] + v[j][3] * v[j][3]); }
;             const float rstd = __builtin_amdgcn_rsqf(wave_sum(s) * (1.f / DMODEL) + EPS);
;             f32x4* o = (f32x4*)(out_p + (size_t)m * DMODEL) + lane;
; #pragma unroll
;             for (int j = 0; j < 8; ++j) { const f32x4 g = *((const f32x4*)final_norm_w + lane + 64 * j); o[64 * j] = v[j] * rstd * g; }
.LBB0_883:
	s_ashr_i32 s0, s0, 6
	s_lshl_b32 s1, s81, 3
	s_add_i32 s4, s1, s0
	s_mov_b64 s[6:7], 0
	s_cmpk_gt_i32 s4, 0x3fff
	s_cbranch_scc1 .LBB0_886
	v_and_b32_e32 v1, 64, v252
	v_add_u32_e32 v1, 64, v1
	v_xor_b32_e32 v2, 1, v252
	v_cmp_lt_i32_e32 vcc, v2, v1
	s_add_u32 s8, s62, s6
	s_addc_u32 s9, s63, s7
	v_cndmask_b32_e32 v2, v252, v2, vcc
	v_lshlrev_b32_e32 v12, 2, v2
	v_xor_b32_e32 v2, 2, v252
	v_cmp_lt_i32_e32 vcc, v2, v1
	s_load_dwordx4 s[0:3], s[8:9], 0x60
	v_and_b32_e32 v0, 63, v0
	v_cndmask_b32_e32 v2, v252, v2, vcc
	v_lshlrev_b32_e32 v13, 2, v2
	v_xor_b32_e32 v2, 4, v252
	v_cmp_lt_i32_e32 vcc, v2, v1
	v_lshlrev_b32_e32 v0, 4, v0
	s_ashr_i32 s5, s4, 31
	v_cndmask_b32_e32 v2, v252, v2, vcc
	v_lshlrev_b32_e32 v14, 2, v2
	v_xor_b32_e32 v2, 8, v252
	v_cmp_lt_i32_e32 vcc, v2, v1
	v_mov_b32_e32 v18, 0x358637bd
	s_movk_i32 s8, 0x1000
	v_cndmask_b32_e32 v2, v252, v2, vcc
	v_lshlrev_b32_e32 v15, 2, v2
	v_xor_b32_e32 v2, 16, v252
	v_cmp_lt_i32_e32 vcc, v2, v1
	s_nop 1
	v_cndmask_b32_e32 v2, v252, v2, vcc
	v_lshlrev_b32_e32 v16, 2, v2
	v_xor_b32_e32 v2, 32, v252
	v_cmp_lt_i32_e32 vcc, v2, v1
	s_nop 1
	v_cndmask_b32_e32 v1, v252, v2, vcc
	v_lshlrev_b32_e32 v17, 2, v1
	v_mov_b32_e32 v1, 0
	s_waitcnt lgkmcnt(0)
	v_lshl_add_u64 v[2:3], s[0:1], 0, v[0:1]
	s_mov_b64 s[0:1], 0x1000
	v_lshl_add_u64 v[4:5], v[2:3], 0, s[0:1]
	s_mov_b64 s[0:1], 0x1400
	v_lshl_add_u64 v[6:7], v[2:3], 0, s[0:1]
	s_mov_b64 s[0:1], 0x1800
	v_lshl_add_u64 v[8:9], v[2:3], 0, s[0:1]
	s_mov_b64 s[0:1], 0x1c00
	v_lshl_add_u64 v[10:11], v[2:3], 0, s[0:1]
	s_lshl_b64 s[0:1], s[4:5], 13
	s_add_u32 s2, s2, s0
	s_addc_u32 s3, s3, s1
	s_add_u32 s0, s6, s0
	s_addc_u32 s1, s7, s1
	s_add_u32 s6, s48, s0
	s_addc_u32 s7, s49, s1
	s_mov_b32 s5, 0x20e01000
	global_load_dwordx4 v[100:103], v[2:3], off
	global_load_dwordx4 v[104:107], v[2:3], off offset:1024
	global_load_dwordx4 v[108:111], v[2:3], off offset:2048
	global_load_dwordx4 v[112:115], v[2:3], off offset:3072
	global_load_dwordx4 v[116:119], v[4:5], off
	global_load_dwordx4 v[120:123], v[6:7], off
	global_load_dwordx4 v[124:127], v[8:9], off
	global_load_dwordx4 v[128:131], v[10:11], off
; __device__ __forceinline__ float wave_sum(float v) {
; #pragma unroll
;     for (int o = 1; o < 64; o <<= 1) v += __shfl_xor(v, o);
;     return v;
; __global__ void __launch_bounds__(NWAVES * 64, 2) mk_fwd(Args args) {
;     ...
;         for (int m = gw; m < SEQ; m += NGW) {
;             const f32x4* xr = (const f32x4*)(XR + (size_t)m * DMODEL) + lane;
;             f32x4 v[8]; float s = 0.f;
; #pragma unroll
;             for (int j = 0; j < 8; ++j) { v[j] = xr[64 * j]; s += (v[j][0] * v[j][0] + v[j][1] * v[j][1]) + (v[j][2] * v[j][2] + v[j][3] * v[j][3]); }
;             const float rstd = __builtin_amdgcn_rsqf(wave_sum(s) * (1.f / DMODEL) + EPS);
;             f32x4* o = (f32x4*)(out_p + (size_t)m * DMODEL) + lane;
; #pragma unroll
;             for (int j = 0; j < 8; ++j) { const f32x4 g = *((const f32x4*)final_norm_w + lane + 64 * j); o[64 * j] = v[j] * rstd * g; }
.LBB0_885:
	s_nop 0
	v_lshl_add_u64 v[20:21], s[6:7], 0, v[0:1]
	v_add_co_u32_e64 v54, s[0:1], s5, v20
	v_add_co_u32_e32 v52, vcc, 0x20e00000, v20
	s_nop 0
	v_addc_co_u32_e64 v55, s[0:1], 0, v21, s[0:1]
	v_addc_co_u32_e32 v53, vcc, 0, v21, vcc
	global_load_dwordx4 v[20:23], v[54:55], off
	global_load_dwordx4 v[24:27], v[54:55], off offset:1024
	global_load_dwordx4 v[28:31], v[54:55], off offset:2048
	global_load_dwordx4 v[32:35], v[52:53], off
	global_load_dwordx4 v[36:39], v[52:53], off offset:1024
	global_load_dwordx4 v[40:43], v[52:53], off offset:2048
	global_load_dwordx4 v[44:47], v[52:53], off offset:3072
	global_load_dwordx4 v[48:51], v[54:55], off offset:3072
	v_lshl_add_u64 v[56:57], s[2:3], 0, v[0:1]
	s_add_i32 s4, s4, s58
	s_add_u32 s2, s2, s60
	s_addc_u32 s3, s3, s61
	s_add_u32 s6, s6, s60
	s_addc_u32 s7, s7, s61
	s_cmpk_lt_i32 s4, 0x4000
	s_waitcnt vmcnt(0)
	v_mul_f32_e32 v81, v21, v21
	v_pk_mul_f32 v[58:59], v[26:27], v[26:27]
	v_pk_mul_f32 v[60:61], v[24:25], v[24:25]
	v_mul_f32_e32 v62, v29, v29
	v_mul_f32_e32 v64, v31, v31
	v_mov_b32_e32 v68, v33
	v_mov_b32_e32 v69, v37
	v_mov_b32_e32 v72, v35
	v_mov_b32_e32 v73, v39
	v_mul_f32_e32 v88, v50, v50
	v_mul_f32_e32 v89, v51, v51
	v_mov_b32_e32 v66, v32
	v_mov_b32_e32 v67, v36
	v_mov_b32_e32 v70, v34
	v_mov_b32_e32 v71, v38
	v_pk_mul_f32 v[74:75], v[42:43], v[42:43]
	v_pk_mul_f32 v[76:77], v[40:41], v[40:41]
	v_pk_mov_b32 v[82:83], v[60:61], v[58:59] op_sel:[1,0]
	v_mov_b32_e32 v61, v59
	v_pk_fma_f32 v[58:59], v[28:29], v[28:29], v[62:63] op_sel_hi:[1,1,0]
	v_pk_fma_f32 v[62:63], v[30:31], v[30:31], v[64:65] op_sel_hi:[1,1,0]
	v_pk_mul_f32 v[64:65], v[68:69], v[68:69]
	v_pk_mul_f32 v[68:69], v[72:73], v[72:73]
	v_pk_mov_b32 v[72:73], v[76:77], v[74:75] op_sel:[1,0]
	v_mov_b32_e32 v77, v75
	v_mov_b32_e32 v59, v88
	v_mov_b32_e32 v63, v89
	v_pk_fma_f32 v[64:65], v[66:67], v[66:67], v[64:65]
	v_pk_fma_f32 v[66:67], v[70:71], v[70:71], v[68:69]
	v_mul_f32_e32 v78, v45, v45
	v_mul_f32_e32 v80, v47, v47
	v_pk_add_f32 v[68:69], v[72:73], v[76:77]
	v_pk_add_f32 v[58:59], v[58:59], v[62:63]
	v_pk_add_f32 v[62:63], v[64:65], v[66:67]
	v_mul_f32_e32 v19, v20, v20
	v_mul_f32_e32 v84, v22, v22
	v_mul_f32_e32 v85, v23, v23
	v_pk_fma_f32 v[74:75], v[44:45], v[44:45], v[78:79] op_sel_hi:[1,1,0]
	v_pk_fma_f32 v[78:79], v[46:47], v[46:47], v[80:81] op_sel_hi:[1,1,0]
	v_pk_add_f32 v[64:65], v[68:69], v[68:69] op_sel:[0,1] op_sel_hi:[1,0]
	v_pk_add_f32 v[62:63], v[62:63], v[62:63] op_sel:[0,1] op_sel_hi:[1,0]
	v_mov_b32_e32 v75, v84
	v_mov_b32_e32 v79, v85
	v_mov_b32_e32 v65, v81
	v_mov_b32_e32 v63, v19
	v_pk_add_f32 v[66:67], v[74:75], v[78:79]
	v_pk_add_f32 v[62:63], v[62:63], v[64:65]
	v_pk_add_f32 v[60:61], v[82:83], v[60:61]
	v_pk_add_f32 v[62:63], v[62:63], v[66:67]
	v_mul_f32_e32 v86, v48, v48
	v_mul_f32_e32 v87, v49, v49
	v_pk_add_f32 v[60:61], v[60:61], v[60:61] op_sel:[0,1] op_sel_hi:[1,0]
	v_pk_add_f32 v[62:63], v[62:63], v[62:63] op_sel:[0,1] op_sel_hi:[1,0]
	v_mov_b32_e32 v61, v87
	v_mov_b32_e32 v63, v86
	v_pk_add_f32 v[60:61], v[62:63], v[60:61]
	s_nop 0
	v_pk_add_f32 v[58:59], v[60:61], v[58:59]
	s_nop 0
	v_add_f32_e32 v19, v58, v59
	ds_bpermute_b32 v58, v12, v19
	s_waitcnt lgkmcnt(0)
	v_add_f32_e32 v19, v19, v58
	ds_bpermute_b32 v58, v13, v19
	s_waitcnt lgkmcnt(0)
	v_add_f32_e32 v19, v19, v58
	ds_bpermute_b32 v58, v14, v19
	s_waitcnt lgkmcnt(0)
	v_add_f32_e32 v19, v19, v58
	ds_bpermute_b32 v58, v15, v19
	s_waitcnt lgkmcnt(0)
	v_add_f32_e32 v19, v19, v58
	ds_bpermute_b32 v58, v16, v19
	s_waitcnt lgkmcnt(0)
	v_add_f32_e32 v19, v19, v58
	ds_bpermute_b32 v58, v17, v19
	s_waitcnt lgkmcnt(0)
	v_add_f32_e32 v19, v19, v58
	v_fmamk_f32 v19, v19, 0x3a000000, v18
	v_rsq_f32_e32 v58, v19
	s_nop 0
	v_pk_mul_f32 v[32:33], v[58:59], v[32:33] op_sel_hi:[0,1]
	v_pk_mul_f32 v[34:35], v[58:59], v[34:35] op_sel_hi:[0,1]
	v_pk_mul_f32 v[34:35], v[102:103], v[34:35]
	v_pk_mul_f32 v[32:33], v[100:101], v[32:33]
	global_store_dwordx4 v[56:57], v[32:35], off
	v_pk_mul_f32 v[38:39], v[58:59], v[38:39] op_sel_hi:[0,1]
	v_pk_mul_f32 v[36:37], v[58:59], v[36:37] op_sel_hi:[0,1]
	v_pk_mul_f32 v[22:23], v[58:59], v[22:23] op_sel_hi:[0,1]
	v_pk_mul_f32 v[20:21], v[58:59], v[20:21] op_sel_hi:[0,1]
	v_pk_mul_f32 v[26:27], v[58:59], v[26:27] op_sel_hi:[0,1]
	v_pk_mul_f32 v[24:25], v[58:59], v[24:25] op_sel_hi:[0,1]
	v_pk_mul_f32 v[32:33], v[104:105], v[36:37]
	v_pk_mul_f32 v[34:35], v[106:107], v[38:39]
	global_store_dwordx4 v[56:57], v[32:35], off offset:1024
	v_pk_mul_f32 v[36:37], v[58:59], v[42:43] op_sel_hi:[0,1]
	v_pk_mul_f32 v[38:39], v[58:59], v[40:41] op_sel_hi:[0,1]
	v_pk_mul_f32 v[32:33], v[108:109], v[38:39]
	v_pk_mul_f32 v[34:35], v[110:111], v[36:37]
	global_store_dwordx4 v[56:57], v[32:35], off offset:2048
	v_pk_mul_f32 v[36:37], v[58:59], v[46:47] op_sel_hi:[0,1]
	v_pk_mul_f32 v[38:39], v[58:59], v[44:45] op_sel_hi:[0,1]
	v_pk_mul_f32 v[32:33], v[112:113], v[38:39]
	v_pk_mul_f32 v[34:35], v[114:115], v[36:37]
	global_store_dwordx4 v[56:57], v[32:35], off offset:3072
	v_add_co_u32_e32 v36, vcc, s8, v56
	v_pk_mul_f32 v[20:21], v[116:117], v[20:21]
	v_addc_co_u32_e32 v37, vcc, 0, v57, vcc
	v_pk_mul_f32 v[22:23], v[118:119], v[22:23]
	global_store_dwordx4 v[36:37], v[20:23], off
	s_nop 1
	v_pk_mul_f32 v[20:21], v[120:121], v[24:25]
	v_pk_mul_f32 v[22:23], v[122:123], v[26:27]
	global_store_dwordx4 v[36:37], v[20:23], off offset:1024
	v_pk_mul_f32 v[24:25], v[58:59], v[30:31] op_sel_hi:[0,1]
	v_pk_mul_f32 v[26:27], v[58:59], v[28:29] op_sel_hi:[0,1]
	v_pk_mul_f32 v[20:21], v[124:125], v[26:27]
	v_pk_mul_f32 v[22:23], v[126:127], v[24:25]
	global_store_dwordx4 v[36:37], v[20:23], off offset:2048
	v_pk_mul_f32 v[24:25], v[58:59], v[50:51] op_sel_hi:[0,1]
	v_pk_mul_f32 v[26:27], v[58:59], v[48:49] op_sel_hi:[0,1]
	v_pk_mul_f32 v[20:21], v[128:129], v[26:27]
	v_pk_mul_f32 v[22:23], v[130:131], v[24:25]
	global_store_dwordx4 v[36:37], v[20:23], off offset:3072
	s_cbranch_scc1 .LBB0_885
